# GEMM K-loops without the per-segment s_setprio toggles
# baseline (speedup 1.0000x reference)
; #define PG8_STAGE(bufoff, gbase, voff) do { _Pragma("unroll") for (int _i = 0; _i < 2; ++_i) \
;         __builtin_amdgcn_global_load_lds((const unsigned*)((const char*)(gbase) + (voff)[_i]), (PG8_LAS unsigned*)(lds + (bufoff) + ldsw + _i * 8192), 16, 0, 0); } while (0)
; #define PG8_LDA(dst, b, h) do { _Pragma("unroll") for (int m = 0; m < 4; ++m) _Pragma("unroll") for (int k = 0; k < 2; ++k) dst[m][k] = *(const PG8_LAS bf16x8*)(lds + PG8_SA(b, h) + aoff + m * 2048 + k * 1024); } while (0)
; #define PG8_LDB(dst, b, h) do { _Pragma("unroll") for (int n = 0; n < 2; ++n) _Pragma("unroll") for (int k = 0; k < 2; ++k) dst[n][k] = *(const PG8_LAS bf16x8*)(lds + PG8_SB(b, h) + boff + n * 2048 + k * 1024); } while (0)
; #define PG8_MMA(ai, bj, At, Bt) do { __builtin_amdgcn_s_setprio(1); _Pragma("unroll") for (int m = 0; m < 4; ++m) _Pragma("unroll") for (int n = 0; n < 2; ++n) _Pragma("unroll") for (int k = 0; k < 2; ++k) \
;         acc[ai][bj][m][n] = __builtin_amdgcn_mfma_f32_16x16x32_bf16(Bt[n][k], At[m][k], acc[ai][bj][m][n], 0, 0, 0); __builtin_amdgcn_s_setprio(0); } while (0)
; #define PG8_WAIT_V(n) asm volatile("s_waitcnt vmcnt(" #n ")" ::: "memory")
; #define PG8_WAIT_L(n) asm volatile("s_waitcnt lgkmcnt(" #n ")" ::: "memory")
; #define PG8_BAR __builtin_amdgcn_s_barrier()
; #define PG8_SCHED __builtin_amdgcn_sched_barrier(0)
; template <class Epi, class Sched, bool ALIGN_EPI = false>
; __device__ __forceinline__ void gemm_phase(PG8_LAS unsigned char* lds, const Gemm g, const Sched& S, const Epi& E) {
;     ...
;             PG8_LDB(B0, 0, 0); PG8_LDB(B1, 0, 1); PG8_SCHED; PG8_LDA(At, 0, 0); PG8_STAGE(PG8_SA(1, 1), a1 + hstep, voffA);
;             PG8_WAIT_V(8); PG8_WAIT_L(0); PG8_BAR; PG8_MMA(0, 0, At, B0); PG8_MMA(0, 1, At, B1); PG8_BAR; PG8_SCHED;
;             PG8_LDA(At, 0, 1); PG8_STAGE(PG8_SB(0, 0), b2, voffB); PG8_STAGE(PG8_SB(0, 1), b2 + hstep, voffB); PG8_STAGE(PG8_SA(0, 0), a2, voffA);
.LBB0_215:
	s_add_u32 s5, s76, 0xfffc0080
	s_addc_u32 s26, s77, -1
	s_add_i32 s27, 0, 0x10000
	s_cmp_eq_u32 s4, 12
	s_cselect_b32 s79, s21, s26
	s_cselect_b32 s78, s22, s5
	v_add_u32_e32 v140, s27, v143
	s_cselect_b32 s55, s23, s49
	s_cselect_b32 s54, s36, s47
	s_add_i32 s5, 0, 0x14000
	ds_read_b128 v[148:151], v140
	ds_read_b128 v[152:155], v140 offset:1024
	ds_read_b128 v[156:159], v140 offset:2048
	ds_read_b128 v[160:163], v140 offset:3072
	v_add_u32_e32 v140, s5, v143
	ds_read_b128 v[164:167], v140
	ds_read_b128 v[168:171], v140 offset:1024
	ds_read_b128 v[172:175], v140 offset:2048
	ds_read_b128 v[176:179], v140 offset:3072
	v_lshl_add_u64 v[140:141], s[76:77], 0, v[136:137]
	s_add_i32 m0, s11, 0xc000
	ds_read_b128 v[180:183], v146
	ds_read_b128 v[184:187], v146 offset:1024
	ds_read_b128 v[188:191], v146 offset:2048
	ds_read_b128 v[192:195], v146 offset:3072
	ds_read_b128 v[196:199], v146 offset:4096
	ds_read_b128 v[200:203], v146 offset:5120
	ds_read_b128 v[204:207], v146 offset:6144
	ds_read_b128 v[224:227], v146 offset:7168
	global_load_lds_dwordx4 v[140:141], off
	v_lshl_add_u64 v[140:141], s[76:77], 0, v[138:139]
	s_add_i32 m0, s11, 0xe000
	s_nop 0
	global_load_lds_dwordx4 v[140:141], off
	s_waitcnt vmcnt(8)
	s_waitcnt lgkmcnt(0)
	s_barrier
	s_waitcnt lgkmcnt(0)
	v_mfma_f32_16x16x32_bf16 v[126:129], v[148:151], v[180:183], v[126:129]
	v_mfma_f32_16x16x32_bf16 v[122:125], v[156:159], v[180:183], v[122:125]
	v_mfma_f32_16x16x32_bf16 v[110:113], v[148:151], v[188:191], v[110:113]
	v_mfma_f32_16x16x32_bf16 v[106:109], v[156:159], v[188:191], v[106:109]
	v_mfma_f32_16x16x32_bf16 v[94:97], v[148:151], v[196:199], v[94:97]
	v_mfma_f32_16x16x32_bf16 v[90:93], v[156:159], v[196:199], v[90:93]
	v_mfma_f32_16x16x32_bf16 v[78:81], v[148:151], v[204:207], v[78:81]
	v_mfma_f32_16x16x32_bf16 v[74:77], v[156:159], v[204:207], v[74:77]
	v_mfma_f32_16x16x32_bf16 v[126:129], v[152:155], v[184:187], v[126:129]
	v_mfma_f32_16x16x32_bf16 v[122:125], v[160:163], v[184:187], v[122:125]
	v_mfma_f32_16x16x32_bf16 v[110:113], v[152:155], v[192:195], v[110:113]
	v_mfma_f32_16x16x32_bf16 v[106:109], v[160:163], v[192:195], v[106:109]
	v_mfma_f32_16x16x32_bf16 v[94:97], v[152:155], v[200:203], v[94:97]
	v_mfma_f32_16x16x32_bf16 v[90:93], v[160:163], v[200:203], v[90:93]
	v_mfma_f32_16x16x32_bf16 v[78:81], v[152:155], v[224:227], v[78:81]
	v_mfma_f32_16x16x32_bf16 v[74:77], v[160:163], v[224:227], v[74:77]
	v_mfma_f32_16x16x32_bf16 v[118:121], v[164:167], v[180:183], v[118:121]
	v_mfma_f32_16x16x32_bf16 v[114:117], v[172:175], v[180:183], v[114:117]
	v_mfma_f32_16x16x32_bf16 v[102:105], v[164:167], v[188:191], v[102:105]
	v_mfma_f32_16x16x32_bf16 v[98:101], v[172:175], v[188:191], v[98:101]
	v_mfma_f32_16x16x32_bf16 v[86:89], v[164:167], v[196:199], v[86:89]
	v_mfma_f32_16x16x32_bf16 v[82:85], v[172:175], v[196:199], v[82:85]
	v_mfma_f32_16x16x32_bf16 v[70:73], v[164:167], v[204:207], v[70:73]
	v_mfma_f32_16x16x32_bf16 v[66:69], v[172:175], v[204:207], v[66:69]
	v_mfma_f32_16x16x32_bf16 v[118:121], v[168:171], v[184:187], v[118:121]
	v_mfma_f32_16x16x32_bf16 v[114:117], v[176:179], v[184:187], v[114:117]
	v_mfma_f32_16x16x32_bf16 v[102:105], v[168:171], v[192:195], v[102:105]
	v_mfma_f32_16x16x32_bf16 v[98:101], v[176:179], v[192:195], v[98:101]
	v_mfma_f32_16x16x32_bf16 v[86:89], v[168:171], v[200:203], v[86:89]
	v_mfma_f32_16x16x32_bf16 v[82:85], v[176:179], v[200:203], v[82:85]
	v_mfma_f32_16x16x32_bf16 v[70:73], v[168:171], v[224:227], v[70:73]
	v_mfma_f32_16x16x32_bf16 v[66:69], v[176:179], v[224:227], v[66:69]
	s_barrier
	s_add_i32 s26, s27, s6
	v_lshl_add_u64 v[140:141], s[54:55], 0, v[0:1]
	s_mov_b32 m0, s26
	ds_read_b128 v[180:183], v146 offset:16384
	ds_read_b128 v[184:187], v146 offset:17408
	ds_read_b128 v[188:191], v146 offset:18432
	ds_read_b128 v[192:195], v146 offset:19456
	ds_read_b128 v[196:199], v146 offset:20480
	ds_read_b128 v[200:203], v146 offset:21504
	ds_read_b128 v[204:207], v146 offset:22528
	ds_read_b128 v[224:227], v146 offset:23552
	global_load_lds_dwordx4 v[140:141], off
	s_add_i32 m0, s26, 0x2000
	s_add_u32 s80, s54, 0x40000
	v_lshl_add_u64 v[208:209], s[54:55], 0, v[130:131]
	s_addc_u32 s81, s55, 0
	s_add_i32 s5, s5, s6
	global_load_lds_dwordx4 v[208:209], off
	v_lshl_add_u64 v[228:229], s[80:81], 0, v[0:1]
	s_mov_b32 m0, s5
	v_lshl_add_u64 v[230:231], s[78:79], 0, v[132:133]
	global_load_lds_dwordx4 v[228:229], off
	v_lshl_add_u64 v[228:229], s[80:81], 0, v[130:131]
	s_add_i32 m0, s5, 0x2000
	s_nop 0
	global_load_lds_dwordx4 v[228:229], off
	v_lshl_add_u64 v[228:229], s[78:79], 0, v[134:135]
	s_mov_b32 m0, s11
	s_nop 0
	global_load_lds_dwordx4 v[228:229], off
	s_mov_b32 m0, s12
	s_nop 0
	global_load_lds_dwordx4 v[230:231], off
	s_waitcnt vmcnt(8)
	s_waitcnt lgkmcnt(0)
	s_barrier
; #define PG8_STAGE(bufoff, gbase, voff) do { _Pragma("unroll") for (int _i = 0; _i < 2; ++_i) \
;         __builtin_amdgcn_global_load_lds((const unsigned*)((const char*)(gbase) + (voff)[_i]), (PG8_LAS unsigned*)(lds + (bufoff) + ldsw + _i * 8192), 16, 0, 0); } while (0)
; #define PG8_LDA(dst, b, h) do { _Pragma("unroll") for (int m = 0; m < 4; ++m) _Pragma("unroll") for (int k = 0; k < 2; ++k) dst[m][k] = *(const PG8_LAS bf16x8*)(lds + PG8_SA(b, h) + aoff + m * 2048 + k * 1024); } while (0)
; #define PG8_LDB(dst, b, h) do { _Pragma("unroll") for (int n = 0; n < 2; ++n) _Pragma("unroll") for (int k = 0; k < 2; ++k) dst[n][k] = *(const PG8_LAS bf16x8*)(lds + PG8_SB(b, h) + boff + n * 2048 + k * 1024); } while (0)
; #define PG8_MMA(ai, bj, At, Bt) do { __builtin_amdgcn_s_setprio(1); _Pragma("unroll") for (int m = 0; m < 4; ++m) _Pragma("unroll") for (int n = 0; n < 2; ++n) _Pragma("unroll") for (int k = 0; k < 2; ++k) \
;         acc[ai][bj][m][n] = __builtin_amdgcn_mfma_f32_16x16x32_bf16(Bt[n][k], At[m][k], acc[ai][bj][m][n], 0, 0, 0); __builtin_amdgcn_s_setprio(0); } while (0)
; #define PG8_WAIT_V(n) asm volatile("s_waitcnt vmcnt(" #n ")" ::: "memory")
; #define PG8_WAIT_L(n) asm volatile("s_waitcnt lgkmcnt(" #n ")" ::: "memory")
; #define PG8_BAR __builtin_amdgcn_s_barrier()
; #define PG8_SCHED __builtin_amdgcn_sched_barrier(0)
; template <class Epi, class Sched, bool ALIGN_EPI = false>
; __device__ __forceinline__ void gemm_phase(PG8_LAS unsigned char* lds, const Gemm g, const Sched& S, const Epi& E) {
;     ...
;             PG8_WAIT_V(8); PG8_WAIT_L(0); PG8_BAR; PG8_MMA(1, 0, At, B0); PG8_MMA(1, 1, At, B1); PG8_BAR; PG8_SCHED;
;             PG8_LDB(B0, 1, 0); PG8_LDB(B1, 1, 1); PG8_SCHED; PG8_LDA(At, 1, 0); PG8_STAGE(PG8_SA(0, 1), a2 + hstep, voffA);
;             PG8_WAIT_V(8); PG8_WAIT_L(0); PG8_BAR; PG8_MMA(0, 0, At, B0); PG8_MMA(0, 1, At, B1); PG8_BAR; PG8_SCHED;
	s_waitcnt lgkmcnt(0)
	v_mfma_f32_16x16x32_bf16 v[62:65], v[148:151], v[180:183], v[62:65]
	v_mfma_f32_16x16x32_bf16 v[58:61], v[156:159], v[180:183], v[58:61]
	v_mfma_f32_16x16x32_bf16 v[46:49], v[148:151], v[188:191], v[46:49]
	v_mfma_f32_16x16x32_bf16 v[42:45], v[156:159], v[188:191], v[42:45]
	v_mfma_f32_16x16x32_bf16 v[30:33], v[148:151], v[196:199], v[30:33]
	v_mfma_f32_16x16x32_bf16 v[26:29], v[156:159], v[196:199], v[26:29]
	v_mfma_f32_16x16x32_bf16 v[14:17], v[148:151], v[204:207], v[14:17]
	v_mfma_f32_16x16x32_bf16 v[10:13], v[156:159], v[204:207], v[10:13]
	v_mfma_f32_16x16x32_bf16 v[62:65], v[152:155], v[184:187], v[62:65]
	v_mfma_f32_16x16x32_bf16 v[58:61], v[160:163], v[184:187], v[58:61]
	v_mfma_f32_16x16x32_bf16 v[46:49], v[152:155], v[192:195], v[46:49]
	v_mfma_f32_16x16x32_bf16 v[42:45], v[160:163], v[192:195], v[42:45]
	v_mfma_f32_16x16x32_bf16 v[30:33], v[152:155], v[200:203], v[30:33]
	v_mfma_f32_16x16x32_bf16 v[26:29], v[160:163], v[200:203], v[26:29]
	v_mfma_f32_16x16x32_bf16 v[14:17], v[152:155], v[224:227], v[14:17]
	v_mfma_f32_16x16x32_bf16 v[10:13], v[160:163], v[224:227], v[10:13]
	v_mfma_f32_16x16x32_bf16 v[54:57], v[164:167], v[180:183], v[54:57]
	v_mfma_f32_16x16x32_bf16 v[50:53], v[172:175], v[180:183], v[50:53]
	v_mfma_f32_16x16x32_bf16 v[38:41], v[164:167], v[188:191], v[38:41]
	v_mfma_f32_16x16x32_bf16 v[34:37], v[172:175], v[188:191], v[34:37]
	v_mfma_f32_16x16x32_bf16 v[22:25], v[164:167], v[196:199], v[22:25]
	v_mfma_f32_16x16x32_bf16 v[18:21], v[172:175], v[196:199], v[18:21]
	v_mfma_f32_16x16x32_bf16 v[6:9], v[164:167], v[204:207], v[6:9]
	v_mfma_f32_16x16x32_bf16 v[2:5], v[172:175], v[204:207], v[2:5]
	v_mfma_f32_16x16x32_bf16 v[54:57], v[168:171], v[184:187], v[54:57]
	v_mfma_f32_16x16x32_bf16 v[50:53], v[176:179], v[184:187], v[50:53]
	v_mfma_f32_16x16x32_bf16 v[38:41], v[168:171], v[192:195], v[38:41]
	v_mfma_f32_16x16x32_bf16 v[34:37], v[176:179], v[192:195], v[34:37]
	v_mfma_f32_16x16x32_bf16 v[22:25], v[168:171], v[200:203], v[22:25]
	v_mfma_f32_16x16x32_bf16 v[18:21], v[176:179], v[200:203], v[18:21]
	v_mfma_f32_16x16x32_bf16 v[6:9], v[168:171], v[224:227], v[6:9]
	v_mfma_f32_16x16x32_bf16 v[2:5], v[176:179], v[224:227], v[2:5]
	s_barrier
	s_add_i32 s5, 0, 0x18000
	v_add_u32_e32 v147, s5, v143
	s_add_i32 s26, 0, 0x1c000
	ds_read_b128 v[148:151], v147
	ds_read_b128 v[152:155], v147 offset:1024
	ds_read_b128 v[156:159], v147 offset:2048
	ds_read_b128 v[160:163], v147 offset:3072
	v_add_u32_e32 v147, s26, v143
	ds_read_b128 v[164:167], v147
	ds_read_b128 v[168:171], v147 offset:1024
	ds_read_b128 v[172:175], v147 offset:2048
	ds_read_b128 v[176:179], v147 offset:3072
	s_add_u32 s78, s78, 0x40000
	s_addc_u32 s79, s79, 0
	s_mov_b32 m0, s13
	v_lshl_add_u64 v[232:233], s[78:79], 0, v[134:135]
	ds_read_b128 v[180:183], v146 offset:32768
	ds_read_b128 v[184:187], v146 offset:33792
	ds_read_b128 v[188:191], v146 offset:34816
	ds_read_b128 v[192:195], v146 offset:35840
	ds_read_b128 v[196:199], v146 offset:36864
	ds_read_b128 v[200:203], v146 offset:37888
	ds_read_b128 v[204:207], v146 offset:38912
	ds_read_b128 v[224:227], v146 offset:39936
	global_load_lds_dwordx4 v[232:233], off
	v_lshl_add_u64 v[232:233], s[78:79], 0, v[132:133]
	s_mov_b32 m0, s14
	s_nop 0
	global_load_lds_dwordx4 v[232:233], off
	s_waitcnt vmcnt(8)
	s_waitcnt lgkmcnt(0)
	s_barrier
	s_waitcnt lgkmcnt(0)
	v_mfma_f32_16x16x32_bf16 v[126:129], v[148:151], v[180:183], v[126:129]
	v_mfma_f32_16x16x32_bf16 v[122:125], v[156:159], v[180:183], v[122:125]
	v_mfma_f32_16x16x32_bf16 v[110:113], v[148:151], v[188:191], v[110:113]
	v_mfma_f32_16x16x32_bf16 v[106:109], v[156:159], v[188:191], v[106:109]
	v_mfma_f32_16x16x32_bf16 v[94:97], v[148:151], v[196:199], v[94:97]
	v_mfma_f32_16x16x32_bf16 v[90:93], v[156:159], v[196:199], v[90:93]
	v_mfma_f32_16x16x32_bf16 v[78:81], v[148:151], v[204:207], v[78:81]
	v_mfma_f32_16x16x32_bf16 v[74:77], v[156:159], v[204:207], v[74:77]
	v_mfma_f32_16x16x32_bf16 v[126:129], v[152:155], v[184:187], v[126:129]
	v_mfma_f32_16x16x32_bf16 v[122:125], v[160:163], v[184:187], v[122:125]
	v_mfma_f32_16x16x32_bf16 v[110:113], v[152:155], v[192:195], v[110:113]
	v_mfma_f32_16x16x32_bf16 v[106:109], v[160:163], v[192:195], v[106:109]
	v_mfma_f32_16x16x32_bf16 v[94:97], v[152:155], v[200:203], v[94:97]
	v_mfma_f32_16x16x32_bf16 v[90:93], v[160:163], v[200:203], v[90:93]
	v_mfma_f32_16x16x32_bf16 v[78:81], v[152:155], v[224:227], v[78:81]
	v_mfma_f32_16x16x32_bf16 v[74:77], v[160:163], v[224:227], v[74:77]
	v_mfma_f32_16x16x32_bf16 v[118:121], v[164:167], v[180:183], v[118:121]
	v_mfma_f32_16x16x32_bf16 v[114:117], v[172:175], v[180:183], v[114:117]
	v_mfma_f32_16x16x32_bf16 v[102:105], v[164:167], v[188:191], v[102:105]
	v_mfma_f32_16x16x32_bf16 v[98:101], v[172:175], v[188:191], v[98:101]
	v_mfma_f32_16x16x32_bf16 v[86:89], v[164:167], v[196:199], v[86:89]
	v_mfma_f32_16x16x32_bf16 v[82:85], v[172:175], v[196:199], v[82:85]
	v_mfma_f32_16x16x32_bf16 v[70:73], v[164:167], v[204:207], v[70:73]
	v_mfma_f32_16x16x32_bf16 v[66:69], v[172:175], v[204:207], v[66:69]
	v_mfma_f32_16x16x32_bf16 v[118:121], v[168:171], v[184:187], v[118:121]
	v_mfma_f32_16x16x32_bf16 v[114:117], v[176:179], v[184:187], v[114:117]
	v_mfma_f32_16x16x32_bf16 v[102:105], v[168:171], v[192:195], v[102:105]
	v_mfma_f32_16x16x32_bf16 v[98:101], v[176:179], v[192:195], v[98:101]
	v_mfma_f32_16x16x32_bf16 v[86:89], v[168:171], v[200:203], v[86:89]
	v_mfma_f32_16x16x32_bf16 v[82:85], v[176:179], v[200:203], v[82:85]
	v_mfma_f32_16x16x32_bf16 v[70:73], v[168:171], v[224:227], v[70:73]
	v_mfma_f32_16x16x32_bf16 v[66:69], v[176:179], v[224:227], v[66:69]
	s_barrier
; #define PG8_STAGE(bufoff, gbase, voff) do { _Pragma("unroll") for (int _i = 0; _i < 2; ++_i) \
;         __builtin_amdgcn_global_load_lds((const unsigned*)((const char*)(gbase) + (voff)[_i]), (PG8_LAS unsigned*)(lds + (bufoff) + ldsw + _i * 8192), 16, 0, 0); } while (0)
; #define PG8_LDA(dst, b, h) do { _Pragma("unroll") for (int m = 0; m < 4; ++m) _Pragma("unroll") for (int k = 0; k < 2; ++k) dst[m][k] = *(const PG8_LAS bf16x8*)(lds + PG8_SA(b, h) + aoff + m * 2048 + k * 1024); } while (0)
; #define PG8_MMA(ai, bj, At, Bt) do { __builtin_amdgcn_s_setprio(1); _Pragma("unroll") for (int m = 0; m < 4; ++m) _Pragma("unroll") for (int n = 0; n < 2; ++n) _Pragma("unroll") for (int k = 0; k < 2; ++k) \
;         acc[ai][bj][m][n] = __builtin_amdgcn_mfma_f32_16x16x32_bf16(Bt[n][k], At[m][k], acc[ai][bj][m][n], 0, 0, 0); __builtin_amdgcn_s_setprio(0); } while (0)
; #define PG8_WAIT_V(n) asm volatile("s_waitcnt vmcnt(" #n ")" ::: "memory")
; #define PG8_WAIT_L(n) asm volatile("s_waitcnt lgkmcnt(" #n ")" ::: "memory")
; #define PG8_BAR __builtin_amdgcn_s_barrier()
; #define PG8_SCHED __builtin_amdgcn_sched_barrier(0)
; template <class Epi, class Sched, bool ALIGN_EPI = false>
; __device__ __forceinline__ void gemm_phase(PG8_LAS unsigned char* lds, const Gemm g, const Sched& S, const Epi& E) {
;     ...
;             PG8_LDA(At, 1, 1); PG8_STAGE(PG8_SB(1, 0), b3, voffB); PG8_STAGE(PG8_SB(1, 1), b3 + hstep, voffB); PG8_STAGE(PG8_SA(1, 0), a3, voffA);
;             PG8_WAIT_V(8); PG8_WAIT_L(0); PG8_BAR; PG8_MMA(1, 0, At, B0); PG8_MMA(1, 1, At, B1); PG8_BAR; PG8_SCHED;
;         }
;         if constexpr (ALIGN_EPI) { if (wr == 0) PG8_BAR; }
	s_add_i32 s5, s5, s6
	v_lshl_add_u64 v[140:141], v[140:141], 0, s[34:35]
	s_mov_b32 m0, s5
	ds_read_b128 v[180:183], v146 offset:49152
	ds_read_b128 v[184:187], v146 offset:50176
	ds_read_b128 v[188:191], v146 offset:51200
	ds_read_b128 v[192:195], v146 offset:52224
	ds_read_b128 v[196:199], v146 offset:53248
	ds_read_b128 v[200:203], v146 offset:54272
	ds_read_b128 v[204:207], v146 offset:55296
	ds_read_b128 v[224:227], v146 offset:56320
	global_load_lds_dwordx4 v[140:141], off
	s_add_i32 m0, s5, 0x2000
	s_add_u32 s54, s54, 0x40080
	v_lshl_add_u64 v[140:141], v[208:209], 0, s[34:35]
	s_addc_u32 s55, s55, 0
	s_add_i32 s5, s26, s6
	global_load_lds_dwordx4 v[140:141], off
	v_lshl_add_u64 v[140:141], s[54:55], 0, v[0:1]
	s_mov_b32 m0, s5
	s_nop 0
	global_load_lds_dwordx4 v[140:141], off
	v_lshl_add_u64 v[140:141], s[54:55], 0, v[130:131]
	s_add_i32 m0, s5, 0x2000
	s_nop 0
	global_load_lds_dwordx4 v[140:141], off
	v_lshl_add_u64 v[140:141], v[228:229], 0, s[34:35]
	s_mov_b32 m0, s15
	s_nop 0
	global_load_lds_dwordx4 v[140:141], off
	v_lshl_add_u64 v[140:141], v[230:231], 0, s[34:35]
	s_mov_b32 m0, s16
	s_nop 0
	global_load_lds_dwordx4 v[140:141], off
	s_waitcnt vmcnt(8)
	s_waitcnt lgkmcnt(0)
	s_barrier
	s_waitcnt lgkmcnt(0)
	v_mfma_f32_16x16x32_bf16 v[62:65], v[148:151], v[180:183], v[62:65]
	v_mfma_f32_16x16x32_bf16 v[58:61], v[156:159], v[180:183], v[58:61]
	v_mfma_f32_16x16x32_bf16 v[46:49], v[148:151], v[188:191], v[46:49]
	v_mfma_f32_16x16x32_bf16 v[42:45], v[156:159], v[188:191], v[42:45]
	v_mfma_f32_16x16x32_bf16 v[30:33], v[148:151], v[196:199], v[30:33]
	v_mfma_f32_16x16x32_bf16 v[26:29], v[156:159], v[196:199], v[26:29]
	v_mfma_f32_16x16x32_bf16 v[14:17], v[148:151], v[204:207], v[14:17]
	v_mfma_f32_16x16x32_bf16 v[10:13], v[156:159], v[204:207], v[10:13]
	v_mfma_f32_16x16x32_bf16 v[62:65], v[152:155], v[184:187], v[62:65]
	v_mfma_f32_16x16x32_bf16 v[58:61], v[160:163], v[184:187], v[58:61]
	v_mfma_f32_16x16x32_bf16 v[46:49], v[152:155], v[192:195], v[46:49]
	v_mfma_f32_16x16x32_bf16 v[42:45], v[160:163], v[192:195], v[42:45]
	v_mfma_f32_16x16x32_bf16 v[30:33], v[152:155], v[200:203], v[30:33]
	v_mfma_f32_16x16x32_bf16 v[26:29], v[160:163], v[200:203], v[26:29]
	v_mfma_f32_16x16x32_bf16 v[14:17], v[152:155], v[224:227], v[14:17]
	v_mfma_f32_16x16x32_bf16 v[10:13], v[160:163], v[224:227], v[10:13]
	v_mfma_f32_16x16x32_bf16 v[54:57], v[164:167], v[180:183], v[54:57]
	v_mfma_f32_16x16x32_bf16 v[50:53], v[172:175], v[180:183], v[50:53]
	v_mfma_f32_16x16x32_bf16 v[38:41], v[164:167], v[188:191], v[38:41]
	v_mfma_f32_16x16x32_bf16 v[34:37], v[172:175], v[188:191], v[34:37]
	v_mfma_f32_16x16x32_bf16 v[22:25], v[164:167], v[196:199], v[22:25]
	v_mfma_f32_16x16x32_bf16 v[18:21], v[172:175], v[196:199], v[18:21]
	v_mfma_f32_16x16x32_bf16 v[6:9], v[164:167], v[204:207], v[6:9]
	v_mfma_f32_16x16x32_bf16 v[2:5], v[172:175], v[204:207], v[2:5]
	v_mfma_f32_16x16x32_bf16 v[54:57], v[168:171], v[184:187], v[54:57]
	v_mfma_f32_16x16x32_bf16 v[50:53], v[176:179], v[184:187], v[50:53]
	v_mfma_f32_16x16x32_bf16 v[38:41], v[168:171], v[192:195], v[38:41]
	v_mfma_f32_16x16x32_bf16 v[34:37], v[176:179], v[192:195], v[34:37]
	v_mfma_f32_16x16x32_bf16 v[22:25], v[168:171], v[200:203], v[22:25]
	v_mfma_f32_16x16x32_bf16 v[18:21], v[176:179], v[200:203], v[18:21]
	v_mfma_f32_16x16x32_bf16 v[6:9], v[168:171], v[224:227], v[6:9]
	v_mfma_f32_16x16x32_bf16 v[2:5], v[176:179], v[224:227], v[2:5]
	s_barrier
	s_add_i32 s4, s4, 2
	s_add_u32 s76, s76, 0x100
	s_addc_u32 s77, s77, 0
	s_add_u32 s47, s47, 0x100
	s_addc_u32 s49, s49, 0
	s_cmp_gt_u32 s4, 13
	s_cbranch_scc0 .LBB0_215
	s_and_b64 vcc, exec, s[42:43]
	s_cbranch_vccz .LBB0_218
	s_barrier

; #define PG8_STAGE(bufoff, gbase, voff) do { _Pragma("unroll") for (int _i = 0; _i < 2; ++_i) \
;         __builtin_amdgcn_global_load_lds((const unsigned*)((const char*)(gbase) + (voff)[_i]), (PG8_LAS unsigned*)(lds + (bufoff) + ldsw + _i * 8192), 16, 0, 0); } while (0)
; #define PG8_LDA(dst, b, h) do { _Pragma("unroll") for (int m = 0; m < 4; ++m) _Pragma("unroll") for (int k = 0; k < 2; ++k) dst[m][k] = *(const PG8_LAS bf16x8*)(lds + PG8_SA(b, h) + aoff + m * 2048 + k * 1024); } while (0)
; #define PG8_LDB(dst, b, h) do { _Pragma("unroll") for (int n = 0; n < 2; ++n) _Pragma("unroll") for (int k = 0; k < 2; ++k) dst[n][k] = *(const PG8_LAS bf16x8*)(lds + PG8_SB(b, h) + boff + n * 2048 + k * 1024); } while (0)
; #define PG8_MMA(ai, bj, At, Bt) do { __builtin_amdgcn_s_setprio(1); _Pragma("unroll") for (int m = 0; m < 4; ++m) _Pragma("unroll") for (int n = 0; n < 2; ++n) _Pragma("unroll") for (int k = 0; k < 2; ++k) \
;         acc[ai][bj][m][n] = __builtin_amdgcn_mfma_f32_16x16x32_bf16(Bt[n][k], At[m][k], acc[ai][bj][m][n], 0, 0, 0); __builtin_amdgcn_s_setprio(0); } while (0)
; #define PG8_WAIT_V(n) asm volatile("s_waitcnt vmcnt(" #n ")" ::: "memory")
; #define PG8_WAIT_L(n) asm volatile("s_waitcnt lgkmcnt(" #n ")" ::: "memory")
; #define PG8_BAR __builtin_amdgcn_s_barrier()
; template <class Epi, class Sched, bool ALIGN_EPI = false>
; __device__ __forceinline__ void gemm_phase(PG8_LAS unsigned char* lds, const Gemm g, const Sched& S, const Epi& E) {
;     ...
;             const bool last = (t == nt - 2);
;             const char* a1 = cA + (size_t)(t + 1) * kstep;
;             const char* a2 = last ? nA : cA + (size_t)(t + 2) * kstep; const char* b2 = last ? nB : cB + (size_t)(t + 2) * kstep;
;             const char* a3 = a2 + kstep; const char* b3 = b2 + kstep;
;             if constexpr (Epi::MID_T > 0) { if (t == Epi::MID_T) E.mid(acc, cur, wr, fr); }
;             PG8_LDB(B0, 0, 0); PG8_LDB(B1, 0, 1); PG8_SCHED; PG8_LDA(At, 0, 0); PG8_STAGE(PG8_SA(1, 1), a1 + hstep, voffA);
;             PG8_WAIT_V(8); PG8_WAIT_L(0); PG8_BAR; PG8_MMA(0, 0, At, B0); PG8_MMA(0, 1, At, B1); PG8_BAR; PG8_SCHED;
;             PG8_LDA(At, 0, 1); PG8_STAGE(PG8_SB(0, 0), b2, voffB); PG8_STAGE(PG8_SB(0, 1), b2 + hstep, voffB); PG8_STAGE(PG8_SA(0, 0), a2, voffA);
;             PG8_WAIT_V(8); PG8_WAIT_L(0); PG8_BAR; PG8_MMA(1, 0, At, B0); PG8_MMA(1, 1, At, B1); PG8_BAR; PG8_SCHED;
.LBB0_462:
	s_add_u32 s82, s80, 0x100
	s_addc_u32 s83, s81, 0
	s_add_i32 s71, 0, 0x10000
	s_cmp_eq_u32 s5, 40
	s_cselect_b32 s89, s49, s83
	s_cselect_b32 s88, s48, s82
	s_cselect_b32 s55, s79, s36
	s_cselect_b32 s54, s78, s4
	s_add_i32 s91, 0, 0x14000
	v_add_u32_e32 v142, s71, v207
	v_add_u32_e32 v158, s91, v207
	ds_read_b128 v[130:133], v142
	ds_read_b128 v[134:137], v142 offset:1024
	ds_read_b128 v[138:141], v142 offset:2048
	ds_read_b128 v[142:145], v142 offset:3072
	ds_read_b128 v[146:149], v158
	ds_read_b128 v[150:153], v158 offset:1024
	ds_read_b128 v[154:157], v158 offset:2048
	ds_read_b128 v[158:161], v158 offset:3072
	v_lshl_add_u64 v[204:205], s[80:81], 0, v[184:185]
	s_add_i32 m0, s13, 0xc000
	ds_read_b128 v[162:165], v209
	ds_read_b128 v[166:169], v209 offset:1024
	ds_read_b128 v[170:173], v209 offset:2048
	ds_read_b128 v[174:177], v209 offset:3072
	ds_read_b128 v[188:191], v209 offset:4096
	ds_read_b128 v[192:195], v209 offset:5120
	ds_read_b128 v[196:199], v209 offset:6144
	ds_read_b128 v[200:203], v209 offset:7168
	global_load_lds_dwordx4 v[204:205], off
	v_lshl_add_u64 v[204:205], s[80:81], 0, v[186:187]
	s_add_i32 m0, s13, 0xe000
	s_nop 0
	global_load_lds_dwordx4 v[204:205], off
	s_waitcnt vmcnt(8)
	s_waitcnt lgkmcnt(0)
	s_barrier
	s_waitcnt lgkmcnt(0)
	v_mfma_f32_16x16x32_bf16 v[126:129], v[130:133], v[162:165], v[126:129]
	v_mfma_f32_16x16x32_bf16 v[122:125], v[138:141], v[162:165], v[122:125]
	v_mfma_f32_16x16x32_bf16 v[110:113], v[130:133], v[170:173], v[110:113]
	v_mfma_f32_16x16x32_bf16 v[106:109], v[138:141], v[170:173], v[106:109]
	v_mfma_f32_16x16x32_bf16 v[94:97], v[130:133], v[188:191], v[94:97]
	v_mfma_f32_16x16x32_bf16 v[90:93], v[138:141], v[188:191], v[90:93]
	v_mfma_f32_16x16x32_bf16 v[78:81], v[130:133], v[196:199], v[78:81]
	v_mfma_f32_16x16x32_bf16 v[74:77], v[138:141], v[196:199], v[74:77]
	v_mfma_f32_16x16x32_bf16 v[126:129], v[134:137], v[166:169], v[126:129]
	v_mfma_f32_16x16x32_bf16 v[122:125], v[142:145], v[166:169], v[122:125]
	v_mfma_f32_16x16x32_bf16 v[110:113], v[134:137], v[174:177], v[110:113]
	v_mfma_f32_16x16x32_bf16 v[106:109], v[142:145], v[174:177], v[106:109]
	v_mfma_f32_16x16x32_bf16 v[94:97], v[134:137], v[192:195], v[94:97]
	v_mfma_f32_16x16x32_bf16 v[90:93], v[142:145], v[192:195], v[90:93]
	v_mfma_f32_16x16x32_bf16 v[78:81], v[134:137], v[200:203], v[78:81]
	v_mfma_f32_16x16x32_bf16 v[74:77], v[142:145], v[200:203], v[74:77]
	v_mfma_f32_16x16x32_bf16 v[118:121], v[146:149], v[162:165], v[118:121]
	v_mfma_f32_16x16x32_bf16 v[114:117], v[154:157], v[162:165], v[114:117]
	v_mfma_f32_16x16x32_bf16 v[102:105], v[146:149], v[170:173], v[102:105]
	v_mfma_f32_16x16x32_bf16 v[98:101], v[154:157], v[170:173], v[98:101]
	v_mfma_f32_16x16x32_bf16 v[86:89], v[146:149], v[188:191], v[86:89]
	v_mfma_f32_16x16x32_bf16 v[82:85], v[154:157], v[188:191], v[82:85]
	v_mfma_f32_16x16x32_bf16 v[70:73], v[146:149], v[196:199], v[70:73]
	v_mfma_f32_16x16x32_bf16 v[66:69], v[154:157], v[196:199], v[66:69]
	v_mfma_f32_16x16x32_bf16 v[118:121], v[150:153], v[166:169], v[118:121]
	v_mfma_f32_16x16x32_bf16 v[114:117], v[158:161], v[166:169], v[114:117]
	v_mfma_f32_16x16x32_bf16 v[102:105], v[150:153], v[174:177], v[102:105]
	v_mfma_f32_16x16x32_bf16 v[98:101], v[158:161], v[174:177], v[98:101]
	v_mfma_f32_16x16x32_bf16 v[86:89], v[150:153], v[192:195], v[86:89]
	v_mfma_f32_16x16x32_bf16 v[82:85], v[158:161], v[192:195], v[82:85]
	v_mfma_f32_16x16x32_bf16 v[70:73], v[150:153], v[200:203], v[70:73]
	v_mfma_f32_16x16x32_bf16 v[66:69], v[158:161], v[200:203], v[66:69]
	s_barrier
	s_add_i32 s71, s71, s12
	v_lshl_add_u64 v[204:205], s[54:55], 0, v[0:1]
	s_mov_b32 m0, s71
	ds_read_b128 v[162:165], v209 offset:16384
	ds_read_b128 v[166:169], v209 offset:17408
	ds_read_b128 v[170:173], v209 offset:18432
	ds_read_b128 v[174:177], v209 offset:19456
	ds_read_b128 v[188:191], v209 offset:20480
	ds_read_b128 v[192:195], v209 offset:21504
	ds_read_b128 v[196:199], v209 offset:22528
	ds_read_b128 v[200:203], v209 offset:23552
	global_load_lds_dwordx4 v[204:205], off
	s_add_i32 m0, s71, 0x2000
	s_add_u32 s80, s54, 0xb0000
	v_lshl_add_u64 v[224:225], s[54:55], 0, v[178:179]
	s_addc_u32 s81, s55, 0
	s_add_i32 s71, s91, s12
	global_load_lds_dwordx4 v[224:225], off
	v_lshl_add_u64 v[226:227], s[80:81], 0, v[0:1]
	s_mov_b32 m0, s71
	v_lshl_add_u64 v[228:229], s[88:89], 0, v[180:181]
	global_load_lds_dwordx4 v[226:227], off
	v_lshl_add_u64 v[226:227], s[80:81], 0, v[178:179]
	s_add_i32 m0, s71, 0x2000
	s_nop 0
	global_load_lds_dwordx4 v[226:227], off
	v_lshl_add_u64 v[226:227], s[88:89], 0, v[182:183]
	s_mov_b32 m0, s13
	s_nop 0
	global_load_lds_dwordx4 v[226:227], off
	s_mov_b32 m0, s14
	s_nop 0
	global_load_lds_dwordx4 v[228:229], off
	s_waitcnt vmcnt(8)
	s_waitcnt lgkmcnt(0)
	s_barrier
; #define PG8_STAGE(bufoff, gbase, voff) do { _Pragma("unroll") for (int _i = 0; _i < 2; ++_i) \
;         __builtin_amdgcn_global_load_lds((const unsigned*)((const char*)(gbase) + (voff)[_i]), (PG8_LAS unsigned*)(lds + (bufoff) + ldsw + _i * 8192), 16, 0, 0); } while (0)
; #define PG8_LDA(dst, b, h) do { _Pragma("unroll") for (int m = 0; m < 4; ++m) _Pragma("unroll") for (int k = 0; k < 2; ++k) dst[m][k] = *(const PG8_LAS bf16x8*)(lds + PG8_SA(b, h) + aoff + m * 2048 + k * 1024); } while (0)
; #define PG8_LDB(dst, b, h) do { _Pragma("unroll") for (int n = 0; n < 2; ++n) _Pragma("unroll") for (int k = 0; k < 2; ++k) dst[n][k] = *(const PG8_LAS bf16x8*)(lds + PG8_SB(b, h) + boff + n * 2048 + k * 1024); } while (0)
; #define PG8_MMA(ai, bj, At, Bt) do { __builtin_amdgcn_s_setprio(1); _Pragma("unroll") for (int m = 0; m < 4; ++m) _Pragma("unroll") for (int n = 0; n < 2; ++n) _Pragma("unroll") for (int k = 0; k < 2; ++k) \
;         acc[ai][bj][m][n] = __builtin_amdgcn_mfma_f32_16x16x32_bf16(Bt[n][k], At[m][k], acc[ai][bj][m][n], 0, 0, 0); __builtin_amdgcn_s_setprio(0); } while (0)
; #define PG8_WAIT_V(n) asm volatile("s_waitcnt vmcnt(" #n ")" ::: "memory")
; #define PG8_WAIT_L(n) asm volatile("s_waitcnt lgkmcnt(" #n ")" ::: "memory")
; #define PG8_BAR __builtin_amdgcn_s_barrier()
; #define PG8_SCHED __builtin_amdgcn_sched_barrier(0)
; template <class Epi, class Sched, bool ALIGN_EPI = false>
; __device__ __forceinline__ void gemm_phase(PG8_LAS unsigned char* lds, const Gemm g, const Sched& S, const Epi& E) {
;     ...
;             PG8_WAIT_V(8); PG8_WAIT_L(0); PG8_BAR; PG8_MMA(1, 0, At, B0); PG8_MMA(1, 1, At, B1); PG8_BAR; PG8_SCHED;
;             PG8_LDB(B0, 1, 0); PG8_LDB(B1, 1, 1); PG8_SCHED; PG8_LDA(At, 1, 0); PG8_STAGE(PG8_SA(0, 1), a2 + hstep, voffA);
;             PG8_WAIT_V(8); PG8_WAIT_L(0); PG8_BAR; PG8_MMA(0, 0, At, B0); PG8_MMA(0, 1, At, B1); PG8_BAR; PG8_SCHED;
	s_waitcnt lgkmcnt(0)
	v_mfma_f32_16x16x32_bf16 v[62:65], v[130:133], v[162:165], v[62:65]
	v_mfma_f32_16x16x32_bf16 v[58:61], v[138:141], v[162:165], v[58:61]
	v_mfma_f32_16x16x32_bf16 v[46:49], v[130:133], v[170:173], v[46:49]
	v_mfma_f32_16x16x32_bf16 v[42:45], v[138:141], v[170:173], v[42:45]
	v_mfma_f32_16x16x32_bf16 v[30:33], v[130:133], v[188:191], v[30:33]
	v_mfma_f32_16x16x32_bf16 v[26:29], v[138:141], v[188:191], v[26:29]
	v_mfma_f32_16x16x32_bf16 v[14:17], v[130:133], v[196:199], v[14:17]
	v_mfma_f32_16x16x32_bf16 v[10:13], v[138:141], v[196:199], v[10:13]
	v_mfma_f32_16x16x32_bf16 v[62:65], v[134:137], v[166:169], v[62:65]
	v_mfma_f32_16x16x32_bf16 v[58:61], v[142:145], v[166:169], v[58:61]
	v_mfma_f32_16x16x32_bf16 v[46:49], v[134:137], v[174:177], v[46:49]
	v_mfma_f32_16x16x32_bf16 v[42:45], v[142:145], v[174:177], v[42:45]
	v_mfma_f32_16x16x32_bf16 v[30:33], v[134:137], v[192:195], v[30:33]
	v_mfma_f32_16x16x32_bf16 v[26:29], v[142:145], v[192:195], v[26:29]
	v_mfma_f32_16x16x32_bf16 v[14:17], v[134:137], v[200:203], v[14:17]
	v_mfma_f32_16x16x32_bf16 v[10:13], v[142:145], v[200:203], v[10:13]
	v_mfma_f32_16x16x32_bf16 v[54:57], v[146:149], v[162:165], v[54:57]
	v_mfma_f32_16x16x32_bf16 v[50:53], v[154:157], v[162:165], v[50:53]
	v_mfma_f32_16x16x32_bf16 v[38:41], v[146:149], v[170:173], v[38:41]
	v_mfma_f32_16x16x32_bf16 v[34:37], v[154:157], v[170:173], v[34:37]
	v_mfma_f32_16x16x32_bf16 v[22:25], v[146:149], v[188:191], v[22:25]
	v_mfma_f32_16x16x32_bf16 v[18:21], v[154:157], v[188:191], v[18:21]
	v_mfma_f32_16x16x32_bf16 v[6:9], v[146:149], v[196:199], v[6:9]
	v_mfma_f32_16x16x32_bf16 v[2:5], v[154:157], v[196:199], v[2:5]
	v_mfma_f32_16x16x32_bf16 v[54:57], v[150:153], v[166:169], v[54:57]
	v_mfma_f32_16x16x32_bf16 v[50:53], v[158:161], v[166:169], v[50:53]
	v_mfma_f32_16x16x32_bf16 v[38:41], v[150:153], v[174:177], v[38:41]
	v_mfma_f32_16x16x32_bf16 v[34:37], v[158:161], v[174:177], v[34:37]
	v_mfma_f32_16x16x32_bf16 v[22:25], v[150:153], v[192:195], v[22:25]
	v_mfma_f32_16x16x32_bf16 v[18:21], v[158:161], v[192:195], v[18:21]
	v_mfma_f32_16x16x32_bf16 v[6:9], v[150:153], v[200:203], v[6:9]
	v_mfma_f32_16x16x32_bf16 v[2:5], v[158:161], v[200:203], v[2:5]
	s_barrier
	s_add_i32 s71, 0, 0x18000
	s_add_i32 s91, 0, 0x1c000
	v_add_u32_e32 v142, s71, v207
	v_add_u32_e32 v158, s91, v207
	ds_read_b128 v[130:133], v142
	ds_read_b128 v[134:137], v142 offset:1024
	ds_read_b128 v[138:141], v142 offset:2048
	ds_read_b128 v[142:145], v142 offset:3072
	ds_read_b128 v[146:149], v158
	ds_read_b128 v[150:153], v158 offset:1024
	ds_read_b128 v[154:157], v158 offset:2048
	ds_read_b128 v[158:161], v158 offset:3072
	s_add_u32 s80, s88, 0xb0000
	s_addc_u32 s81, s89, 0
	s_mov_b32 m0, s15
	v_lshl_add_u64 v[230:231], s[80:81], 0, v[182:183]
	ds_read_b128 v[162:165], v209 offset:32768
	ds_read_b128 v[166:169], v209 offset:33792
	ds_read_b128 v[170:173], v209 offset:34816
	ds_read_b128 v[174:177], v209 offset:35840
	ds_read_b128 v[188:191], v209 offset:36864
	ds_read_b128 v[192:195], v209 offset:37888
	ds_read_b128 v[196:199], v209 offset:38912
	ds_read_b128 v[200:203], v209 offset:39936
	global_load_lds_dwordx4 v[230:231], off
	v_lshl_add_u64 v[230:231], s[80:81], 0, v[180:181]
	s_mov_b32 m0, s16
	s_nop 0
	global_load_lds_dwordx4 v[230:231], off
	s_waitcnt vmcnt(8)
	s_waitcnt lgkmcnt(0)
	s_barrier
	s_waitcnt lgkmcnt(0)
	v_mfma_f32_16x16x32_bf16 v[126:129], v[130:133], v[162:165], v[126:129]
	v_mfma_f32_16x16x32_bf16 v[122:125], v[138:141], v[162:165], v[122:125]
	v_mfma_f32_16x16x32_bf16 v[110:113], v[130:133], v[170:173], v[110:113]
	v_mfma_f32_16x16x32_bf16 v[106:109], v[138:141], v[170:173], v[106:109]
	v_mfma_f32_16x16x32_bf16 v[94:97], v[130:133], v[188:191], v[94:97]
	v_mfma_f32_16x16x32_bf16 v[90:93], v[138:141], v[188:191], v[90:93]
	v_mfma_f32_16x16x32_bf16 v[78:81], v[130:133], v[196:199], v[78:81]
	v_mfma_f32_16x16x32_bf16 v[74:77], v[138:141], v[196:199], v[74:77]
	v_mfma_f32_16x16x32_bf16 v[126:129], v[134:137], v[166:169], v[126:129]
	v_mfma_f32_16x16x32_bf16 v[122:125], v[142:145], v[166:169], v[122:125]
	v_mfma_f32_16x16x32_bf16 v[110:113], v[134:137], v[174:177], v[110:113]
	v_mfma_f32_16x16x32_bf16 v[106:109], v[142:145], v[174:177], v[106:109]
	v_mfma_f32_16x16x32_bf16 v[94:97], v[134:137], v[192:195], v[94:97]
	v_mfma_f32_16x16x32_bf16 v[90:93], v[142:145], v[192:195], v[90:93]
	v_mfma_f32_16x16x32_bf16 v[78:81], v[134:137], v[200:203], v[78:81]
	v_mfma_f32_16x16x32_bf16 v[74:77], v[142:145], v[200:203], v[74:77]
	v_mfma_f32_16x16x32_bf16 v[118:121], v[146:149], v[162:165], v[118:121]
	v_mfma_f32_16x16x32_bf16 v[114:117], v[154:157], v[162:165], v[114:117]
	v_mfma_f32_16x16x32_bf16 v[102:105], v[146:149], v[170:173], v[102:105]
	v_mfma_f32_16x16x32_bf16 v[98:101], v[154:157], v[170:173], v[98:101]
	v_mfma_f32_16x16x32_bf16 v[86:89], v[146:149], v[188:191], v[86:89]
	v_mfma_f32_16x16x32_bf16 v[82:85], v[154:157], v[188:191], v[82:85]
	v_mfma_f32_16x16x32_bf16 v[70:73], v[146:149], v[196:199], v[70:73]
	v_mfma_f32_16x16x32_bf16 v[66:69], v[154:157], v[196:199], v[66:69]
	v_mfma_f32_16x16x32_bf16 v[118:121], v[150:153], v[166:169], v[118:121]
	v_mfma_f32_16x16x32_bf16 v[114:117], v[158:161], v[166:169], v[114:117]
	v_mfma_f32_16x16x32_bf16 v[102:105], v[150:153], v[174:177], v[102:105]
	v_mfma_f32_16x16x32_bf16 v[98:101], v[158:161], v[174:177], v[98:101]
	v_mfma_f32_16x16x32_bf16 v[86:89], v[150:153], v[192:195], v[86:89]
	v_mfma_f32_16x16x32_bf16 v[82:85], v[158:161], v[192:195], v[82:85]
	v_mfma_f32_16x16x32_bf16 v[70:73], v[150:153], v[200:203], v[70:73]
	v_mfma_f32_16x16x32_bf16 v[66:69], v[158:161], v[200:203], v[66:69]
	s_barrier
; #define PG8_STAGE(bufoff, gbase, voff) do { _Pragma("unroll") for (int _i = 0; _i < 2; ++_i) \
;         __builtin_amdgcn_global_load_lds((const unsigned*)((const char*)(gbase) + (voff)[_i]), (PG8_LAS unsigned*)(lds + (bufoff) + ldsw + _i * 8192), 16, 0, 0); } while (0)
; #define PG8_LDA(dst, b, h) do { _Pragma("unroll") for (int m = 0; m < 4; ++m) _Pragma("unroll") for (int k = 0; k < 2; ++k) dst[m][k] = *(const PG8_LAS bf16x8*)(lds + PG8_SA(b, h) + aoff + m * 2048 + k * 1024); } while (0)
; #define PG8_MMA(ai, bj, At, Bt) do { __builtin_amdgcn_s_setprio(1); _Pragma("unroll") for (int m = 0; m < 4; ++m) _Pragma("unroll") for (int n = 0; n < 2; ++n) _Pragma("unroll") for (int k = 0; k < 2; ++k) \
;         acc[ai][bj][m][n] = __builtin_amdgcn_mfma_f32_16x16x32_bf16(Bt[n][k], At[m][k], acc[ai][bj][m][n], 0, 0, 0); __builtin_amdgcn_s_setprio(0); } while (0)
; #define PG8_WAIT_V(n) asm volatile("s_waitcnt vmcnt(" #n ")" ::: "memory")
; #define PG8_WAIT_L(n) asm volatile("s_waitcnt lgkmcnt(" #n ")" ::: "memory")
; #define PG8_BAR __builtin_amdgcn_s_barrier()
; #define PG8_SCHED __builtin_amdgcn_sched_barrier(0)
; template <class Epi, class Sched, bool ALIGN_EPI = false>
; __device__ __forceinline__ void gemm_phase(PG8_LAS unsigned char* lds, const Gemm g, const Sched& S, const Epi& E) {
;     ...
;             PG8_LDA(At, 1, 1); PG8_STAGE(PG8_SB(1, 0), b3, voffB); PG8_STAGE(PG8_SB(1, 1), b3 + hstep, voffB); PG8_STAGE(PG8_SA(1, 0), a3, voffA);
;             PG8_WAIT_V(8); PG8_WAIT_L(0); PG8_BAR; PG8_MMA(1, 0, At, B0); PG8_MMA(1, 1, At, B1); PG8_BAR; PG8_SCHED;
;         }
;         if constexpr (ALIGN_EPI) { if (wr == 0) PG8_BAR; }
	s_add_i32 s71, s71, s12
	v_lshl_add_u64 v[204:205], v[204:205], 0, s[34:35]
	s_mov_b32 m0, s71
	ds_read_b128 v[162:165], v209 offset:49152
	ds_read_b128 v[166:169], v209 offset:50176
	ds_read_b128 v[170:173], v209 offset:51200
	ds_read_b128 v[174:177], v209 offset:52224
	ds_read_b128 v[188:191], v209 offset:53248
	ds_read_b128 v[192:195], v209 offset:54272
	ds_read_b128 v[196:199], v209 offset:55296
	ds_read_b128 v[200:203], v209 offset:56320
	global_load_lds_dwordx4 v[204:205], off
	s_add_i32 m0, s71, 0x2000
	s_add_u32 s54, s54, 0xb0080
	v_lshl_add_u64 v[204:205], v[224:225], 0, s[34:35]
	s_addc_u32 s55, s55, 0
	s_add_i32 s71, s91, s12
	global_load_lds_dwordx4 v[204:205], off
	v_lshl_add_u64 v[204:205], s[54:55], 0, v[0:1]
	s_mov_b32 m0, s71
	s_nop 0
	global_load_lds_dwordx4 v[204:205], off
	v_lshl_add_u64 v[204:205], s[54:55], 0, v[178:179]
	s_add_i32 m0, s71, 0x2000
	s_nop 0
	global_load_lds_dwordx4 v[204:205], off
	v_lshl_add_u64 v[204:205], v[226:227], 0, s[34:35]
	s_mov_b32 m0, s18
	s_nop 0
	global_load_lds_dwordx4 v[204:205], off
	v_lshl_add_u64 v[204:205], v[228:229], 0, s[34:35]
	s_mov_b32 m0, s19
	s_nop 0
	global_load_lds_dwordx4 v[204:205], off
	s_waitcnt vmcnt(8)
	s_waitcnt lgkmcnt(0)
	s_barrier
	s_waitcnt lgkmcnt(0)
	v_mfma_f32_16x16x32_bf16 v[62:65], v[130:133], v[162:165], v[62:65]
	v_mfma_f32_16x16x32_bf16 v[58:61], v[138:141], v[162:165], v[58:61]
	v_mfma_f32_16x16x32_bf16 v[46:49], v[130:133], v[170:173], v[46:49]
	v_mfma_f32_16x16x32_bf16 v[42:45], v[138:141], v[170:173], v[42:45]
	v_mfma_f32_16x16x32_bf16 v[30:33], v[130:133], v[188:191], v[30:33]
	v_mfma_f32_16x16x32_bf16 v[26:29], v[138:141], v[188:191], v[26:29]
	v_mfma_f32_16x16x32_bf16 v[14:17], v[130:133], v[196:199], v[14:17]
	v_mfma_f32_16x16x32_bf16 v[10:13], v[138:141], v[196:199], v[10:13]
	v_mfma_f32_16x16x32_bf16 v[62:65], v[134:137], v[166:169], v[62:65]
	v_mfma_f32_16x16x32_bf16 v[58:61], v[142:145], v[166:169], v[58:61]
	v_mfma_f32_16x16x32_bf16 v[46:49], v[134:137], v[174:177], v[46:49]
	v_mfma_f32_16x16x32_bf16 v[42:45], v[142:145], v[174:177], v[42:45]
	v_mfma_f32_16x16x32_bf16 v[30:33], v[134:137], v[192:195], v[30:33]
	v_mfma_f32_16x16x32_bf16 v[26:29], v[142:145], v[192:195], v[26:29]
	v_mfma_f32_16x16x32_bf16 v[14:17], v[134:137], v[200:203], v[14:17]
	v_mfma_f32_16x16x32_bf16 v[10:13], v[142:145], v[200:203], v[10:13]
	v_mfma_f32_16x16x32_bf16 v[54:57], v[146:149], v[162:165], v[54:57]
	v_mfma_f32_16x16x32_bf16 v[50:53], v[154:157], v[162:165], v[50:53]
	v_mfma_f32_16x16x32_bf16 v[38:41], v[146:149], v[170:173], v[38:41]
	v_mfma_f32_16x16x32_bf16 v[34:37], v[154:157], v[170:173], v[34:37]
	v_mfma_f32_16x16x32_bf16 v[22:25], v[146:149], v[188:191], v[22:25]
	v_mfma_f32_16x16x32_bf16 v[18:21], v[154:157], v[188:191], v[18:21]
	v_mfma_f32_16x16x32_bf16 v[6:9], v[146:149], v[196:199], v[6:9]
	v_mfma_f32_16x16x32_bf16 v[2:5], v[154:157], v[196:199], v[2:5]
	v_mfma_f32_16x16x32_bf16 v[54:57], v[150:153], v[166:169], v[54:57]
	v_mfma_f32_16x16x32_bf16 v[50:53], v[158:161], v[166:169], v[50:53]
	v_mfma_f32_16x16x32_bf16 v[38:41], v[150:153], v[174:177], v[38:41]
	v_mfma_f32_16x16x32_bf16 v[34:37], v[158:161], v[174:177], v[34:37]
	v_mfma_f32_16x16x32_bf16 v[22:25], v[150:153], v[192:195], v[22:25]
	v_mfma_f32_16x16x32_bf16 v[18:21], v[158:161], v[192:195], v[18:21]
	v_mfma_f32_16x16x32_bf16 v[6:9], v[150:153], v[200:203], v[6:9]
	v_mfma_f32_16x16x32_bf16 v[2:5], v[158:161], v[200:203], v[2:5]
	s_barrier
	s_add_i32 s5, s5, 2
	s_add_u32 s4, s4, 0x100
	s_addc_u32 s36, s36, 0
	s_cmp_gt_u32 s5, 41
	s_mov_b64 s[80:81], s[82:83]
	s_cbranch_scc0 .LBB0_462
	s_and_b64 vcc, exec, s[76:77]
	s_cbranch_vccz .LBB0_465
	s_barrier

; #define PG8_STAGE(bufoff, gbase, voff) do { _Pragma("unroll") for (int _i = 0; _i < 2; ++_i) \
;         __builtin_amdgcn_global_load_lds((const unsigned*)((const char*)(gbase) + (voff)[_i]), (PG8_LAS unsigned*)(lds + (bufoff) + ldsw + _i * 8192), 16, 0, 0); } while (0)
; #define PG8_LDA(dst, b, h) do { _Pragma("unroll") for (int m = 0; m < 4; ++m) _Pragma("unroll") for (int k = 0; k < 2; ++k) dst[m][k] = *(const PG8_LAS bf16x8*)(lds + PG8_SA(b, h) + aoff + m * 2048 + k * 1024); } while (0)
; #define PG8_LDB(dst, b, h) do { _Pragma("unroll") for (int n = 0; n < 2; ++n) _Pragma("unroll") for (int k = 0; k < 2; ++k) dst[n][k] = *(const PG8_LAS bf16x8*)(lds + PG8_SB(b, h) + boff + n * 2048 + k * 1024); } while (0)
; #define PG8_MMA(ai, bj, At, Bt) do { __builtin_amdgcn_s_setprio(1); _Pragma("unroll") for (int m = 0; m < 4; ++m) _Pragma("unroll") for (int n = 0; n < 2; ++n) _Pragma("unroll") for (int k = 0; k < 2; ++k) \
;         acc[ai][bj][m][n] = __builtin_amdgcn_mfma_f32_16x16x32_bf16(Bt[n][k], At[m][k], acc[ai][bj][m][n], 0, 0, 0); __builtin_amdgcn_s_setprio(0); } while (0)
; #define PG8_WAIT_V(n) asm volatile("s_waitcnt vmcnt(" #n ")" ::: "memory")
; #define PG8_WAIT_L(n) asm volatile("s_waitcnt lgkmcnt(" #n ")" ::: "memory")
; #define PG8_BAR __builtin_amdgcn_s_barrier()
; template <class Epi, class Sched, bool ALIGN_EPI = false>
; __device__ __forceinline__ void gemm_phase(PG8_LAS unsigned char* lds, const Gemm g, const Sched& S, const Epi& E) {
;     ...
;             const bool last = (t == nt - 2);
;             const char* a1 = cA + (size_t)(t + 1) * kstep;
;             const char* a2 = last ? nA : cA + (size_t)(t + 2) * kstep; const char* b2 = last ? nB : cB + (size_t)(t + 2) * kstep;
;             const char* a3 = a2 + kstep; const char* b3 = b2 + kstep;
;             if constexpr (Epi::MID_T > 0) { if (t == Epi::MID_T) E.mid(acc, cur, wr, fr); }
;             PG8_LDB(B0, 0, 0); PG8_LDB(B1, 0, 1); PG8_SCHED; PG8_LDA(At, 0, 0); PG8_STAGE(PG8_SA(1, 1), a1 + hstep, voffA);
;             PG8_WAIT_V(8); PG8_WAIT_L(0); PG8_BAR; PG8_MMA(0, 0, At, B0); PG8_MMA(0, 1, At, B1); PG8_BAR; PG8_SCHED;
;             PG8_LDA(At, 0, 1); PG8_STAGE(PG8_SB(0, 0), b2, voffB); PG8_STAGE(PG8_SB(0, 1), b2 + hstep, voffB); PG8_STAGE(PG8_SA(0, 0), a2, voffA);
;             PG8_WAIT_V(8); PG8_WAIT_L(0); PG8_BAR; PG8_MMA(1, 0, At, B0); PG8_MMA(1, 1, At, B1); PG8_BAR; PG8_SCHED;
.LBB0_558:
	s_add_u32 s76, s52, 0x100
	s_addc_u32 s77, s53, 0
	s_add_i32 s71, 0, 0x10000
	s_cmp_eq_u32 s5, 40
	s_cselect_b32 s79, s49, s77
	s_cselect_b32 s78, s48, s76
	s_cselect_b32 s55, s51, s23
	s_cselect_b32 s54, s50, s4
	s_add_i32 s80, 0, 0x14000
	v_add_u32_e32 v142, s71, v224
	v_add_u32_e32 v158, s80, v224
	ds_read_b128 v[130:133], v142
	ds_read_b128 v[134:137], v142 offset:1024
	ds_read_b128 v[138:141], v142 offset:2048
	ds_read_b128 v[142:145], v142 offset:3072
	ds_read_b128 v[146:149], v158
	ds_read_b128 v[150:153], v158 offset:1024
	ds_read_b128 v[154:157], v158 offset:2048
	ds_read_b128 v[158:161], v158 offset:3072
	v_lshl_add_u64 v[204:205], s[52:53], 0, v[184:185]
	s_add_i32 m0, s13, 0xc000
	ds_read_b128 v[162:165], v226
	ds_read_b128 v[166:169], v226 offset:1024
	ds_read_b128 v[170:173], v226 offset:2048
	ds_read_b128 v[174:177], v226 offset:3072
	ds_read_b128 v[188:191], v226 offset:4096
	ds_read_b128 v[192:195], v226 offset:5120
	ds_read_b128 v[196:199], v226 offset:6144
	ds_read_b128 v[200:203], v226 offset:7168
	global_load_lds_dwordx4 v[204:205], off
	v_lshl_add_u64 v[204:205], s[52:53], 0, v[186:187]
	s_add_i32 m0, s13, 0xe000
	s_nop 0
	global_load_lds_dwordx4 v[204:205], off
	s_waitcnt vmcnt(8)
	s_waitcnt lgkmcnt(0)
	s_barrier
	s_waitcnt lgkmcnt(0)
	v_mfma_f32_16x16x32_bf16 v[126:129], v[130:133], v[162:165], v[126:129]
	v_mfma_f32_16x16x32_bf16 v[122:125], v[138:141], v[162:165], v[122:125]
	v_mfma_f32_16x16x32_bf16 v[110:113], v[130:133], v[170:173], v[110:113]
	v_mfma_f32_16x16x32_bf16 v[106:109], v[138:141], v[170:173], v[106:109]
	v_mfma_f32_16x16x32_bf16 v[94:97], v[130:133], v[188:191], v[94:97]
	v_mfma_f32_16x16x32_bf16 v[90:93], v[138:141], v[188:191], v[90:93]
	v_mfma_f32_16x16x32_bf16 v[78:81], v[130:133], v[196:199], v[78:81]
	v_mfma_f32_16x16x32_bf16 v[74:77], v[138:141], v[196:199], v[74:77]
	v_mfma_f32_16x16x32_bf16 v[126:129], v[134:137], v[166:169], v[126:129]
	v_mfma_f32_16x16x32_bf16 v[122:125], v[142:145], v[166:169], v[122:125]
	v_mfma_f32_16x16x32_bf16 v[110:113], v[134:137], v[174:177], v[110:113]
	v_mfma_f32_16x16x32_bf16 v[106:109], v[142:145], v[174:177], v[106:109]
	v_mfma_f32_16x16x32_bf16 v[94:97], v[134:137], v[192:195], v[94:97]
	v_mfma_f32_16x16x32_bf16 v[90:93], v[142:145], v[192:195], v[90:93]
	v_mfma_f32_16x16x32_bf16 v[78:81], v[134:137], v[200:203], v[78:81]
	v_mfma_f32_16x16x32_bf16 v[74:77], v[142:145], v[200:203], v[74:77]
	v_mfma_f32_16x16x32_bf16 v[118:121], v[146:149], v[162:165], v[118:121]
	v_mfma_f32_16x16x32_bf16 v[114:117], v[154:157], v[162:165], v[114:117]
	v_mfma_f32_16x16x32_bf16 v[102:105], v[146:149], v[170:173], v[102:105]
	v_mfma_f32_16x16x32_bf16 v[98:101], v[154:157], v[170:173], v[98:101]
	v_mfma_f32_16x16x32_bf16 v[86:89], v[146:149], v[188:191], v[86:89]
	v_mfma_f32_16x16x32_bf16 v[82:85], v[154:157], v[188:191], v[82:85]
	v_mfma_f32_16x16x32_bf16 v[70:73], v[146:149], v[196:199], v[70:73]
	v_mfma_f32_16x16x32_bf16 v[66:69], v[154:157], v[196:199], v[66:69]
	v_mfma_f32_16x16x32_bf16 v[118:121], v[150:153], v[166:169], v[118:121]
	v_mfma_f32_16x16x32_bf16 v[114:117], v[158:161], v[166:169], v[114:117]
	v_mfma_f32_16x16x32_bf16 v[102:105], v[150:153], v[174:177], v[102:105]
	v_mfma_f32_16x16x32_bf16 v[98:101], v[158:161], v[174:177], v[98:101]
	v_mfma_f32_16x16x32_bf16 v[86:89], v[150:153], v[192:195], v[86:89]
	v_mfma_f32_16x16x32_bf16 v[82:85], v[158:161], v[192:195], v[82:85]
	v_mfma_f32_16x16x32_bf16 v[70:73], v[150:153], v[200:203], v[70:73]
	v_mfma_f32_16x16x32_bf16 v[66:69], v[158:161], v[200:203], v[66:69]
	s_barrier
	s_add_i32 s52, s71, s12
	v_lshl_add_u64 v[204:205], s[54:55], 0, v[0:1]
	s_mov_b32 m0, s52
	ds_read_b128 v[162:165], v226 offset:16384
	ds_read_b128 v[166:169], v226 offset:17408
	ds_read_b128 v[170:173], v226 offset:18432
	ds_read_b128 v[174:177], v226 offset:19456
	ds_read_b128 v[188:191], v226 offset:20480
	ds_read_b128 v[192:195], v226 offset:21504
	ds_read_b128 v[196:199], v226 offset:22528
	ds_read_b128 v[200:203], v226 offset:23552
	global_load_lds_dwordx4 v[204:205], off
	s_add_i32 m0, s52, 0x2000
	s_add_u32 s52, s54, 0xb0000
	v_lshl_add_u64 v[206:207], s[54:55], 0, v[178:179]
	s_addc_u32 s53, s55, 0
	s_add_i32 s71, s80, s12
	global_load_lds_dwordx4 v[206:207], off
	v_lshl_add_u64 v[208:209], s[52:53], 0, v[0:1]
	s_mov_b32 m0, s71
	v_lshl_add_u64 v[228:229], s[78:79], 0, v[180:181]
	global_load_lds_dwordx4 v[208:209], off
	v_lshl_add_u64 v[208:209], s[52:53], 0, v[178:179]
	s_add_i32 m0, s71, 0x2000
	s_nop 0
	global_load_lds_dwordx4 v[208:209], off
	v_lshl_add_u64 v[208:209], s[78:79], 0, v[182:183]
	s_mov_b32 m0, s13
	s_nop 0
	global_load_lds_dwordx4 v[208:209], off
	s_mov_b32 m0, s14
	s_nop 0
	global_load_lds_dwordx4 v[228:229], off
	s_waitcnt vmcnt(8)
	s_waitcnt lgkmcnt(0)
	s_barrier
; #define PG8_STAGE(bufoff, gbase, voff) do { _Pragma("unroll") for (int _i = 0; _i < 2; ++_i) \
;         __builtin_amdgcn_global_load_lds((const unsigned*)((const char*)(gbase) + (voff)[_i]), (PG8_LAS unsigned*)(lds + (bufoff) + ldsw + _i * 8192), 16, 0, 0); } while (0)
; #define PG8_LDA(dst, b, h) do { _Pragma("unroll") for (int m = 0; m < 4; ++m) _Pragma("unroll") for (int k = 0; k < 2; ++k) dst[m][k] = *(const PG8_LAS bf16x8*)(lds + PG8_SA(b, h) + aoff + m * 2048 + k * 1024); } while (0)
; #define PG8_LDB(dst, b, h) do { _Pragma("unroll") for (int n = 0; n < 2; ++n) _Pragma("unroll") for (int k = 0; k < 2; ++k) dst[n][k] = *(const PG8_LAS bf16x8*)(lds + PG8_SB(b, h) + boff + n * 2048 + k * 1024); } while (0)
; #define PG8_MMA(ai, bj, At, Bt) do { __builtin_amdgcn_s_setprio(1); _Pragma("unroll") for (int m = 0; m < 4; ++m) _Pragma("unroll") for (int n = 0; n < 2; ++n) _Pragma("unroll") for (int k = 0; k < 2; ++k) \
;         acc[ai][bj][m][n] = __builtin_amdgcn_mfma_f32_16x16x32_bf16(Bt[n][k], At[m][k], acc[ai][bj][m][n], 0, 0, 0); __builtin_amdgcn_s_setprio(0); } while (0)
; #define PG8_WAIT_V(n) asm volatile("s_waitcnt vmcnt(" #n ")" ::: "memory")
; #define PG8_WAIT_L(n) asm volatile("s_waitcnt lgkmcnt(" #n ")" ::: "memory")
; #define PG8_BAR __builtin_amdgcn_s_barrier()
; #define PG8_SCHED __builtin_amdgcn_sched_barrier(0)
; template <class Epi, class Sched, bool ALIGN_EPI = false>
; __device__ __forceinline__ void gemm_phase(PG8_LAS unsigned char* lds, const Gemm g, const Sched& S, const Epi& E) {
;     ...
;             PG8_WAIT_V(8); PG8_WAIT_L(0); PG8_BAR; PG8_MMA(1, 0, At, B0); PG8_MMA(1, 1, At, B1); PG8_BAR; PG8_SCHED;
;             PG8_LDB(B0, 1, 0); PG8_LDB(B1, 1, 1); PG8_SCHED; PG8_LDA(At, 1, 0); PG8_STAGE(PG8_SA(0, 1), a2 + hstep, voffA);
;             PG8_WAIT_V(8); PG8_WAIT_L(0); PG8_BAR; PG8_MMA(0, 0, At, B0); PG8_MMA(0, 1, At, B1); PG8_BAR; PG8_SCHED;
	s_waitcnt lgkmcnt(0)
	v_mfma_f32_16x16x32_bf16 v[62:65], v[130:133], v[162:165], v[62:65]
	v_mfma_f32_16x16x32_bf16 v[58:61], v[138:141], v[162:165], v[58:61]
	v_mfma_f32_16x16x32_bf16 v[46:49], v[130:133], v[170:173], v[46:49]
	v_mfma_f32_16x16x32_bf16 v[42:45], v[138:141], v[170:173], v[42:45]
	v_mfma_f32_16x16x32_bf16 v[30:33], v[130:133], v[188:191], v[30:33]
	v_mfma_f32_16x16x32_bf16 v[26:29], v[138:141], v[188:191], v[26:29]
	v_mfma_f32_16x16x32_bf16 v[14:17], v[130:133], v[196:199], v[14:17]
	v_mfma_f32_16x16x32_bf16 v[10:13], v[138:141], v[196:199], v[10:13]
	v_mfma_f32_16x16x32_bf16 v[62:65], v[134:137], v[166:169], v[62:65]
	v_mfma_f32_16x16x32_bf16 v[58:61], v[142:145], v[166:169], v[58:61]
	v_mfma_f32_16x16x32_bf16 v[46:49], v[134:137], v[174:177], v[46:49]
	v_mfma_f32_16x16x32_bf16 v[42:45], v[142:145], v[174:177], v[42:45]
	v_mfma_f32_16x16x32_bf16 v[30:33], v[134:137], v[192:195], v[30:33]
	v_mfma_f32_16x16x32_bf16 v[26:29], v[142:145], v[192:195], v[26:29]
	v_mfma_f32_16x16x32_bf16 v[14:17], v[134:137], v[200:203], v[14:17]
	v_mfma_f32_16x16x32_bf16 v[10:13], v[142:145], v[200:203], v[10:13]
	v_mfma_f32_16x16x32_bf16 v[54:57], v[146:149], v[162:165], v[54:57]
	v_mfma_f32_16x16x32_bf16 v[50:53], v[154:157], v[162:165], v[50:53]
	v_mfma_f32_16x16x32_bf16 v[38:41], v[146:149], v[170:173], v[38:41]
	v_mfma_f32_16x16x32_bf16 v[34:37], v[154:157], v[170:173], v[34:37]
	v_mfma_f32_16x16x32_bf16 v[22:25], v[146:149], v[188:191], v[22:25]
	v_mfma_f32_16x16x32_bf16 v[18:21], v[154:157], v[188:191], v[18:21]
	v_mfma_f32_16x16x32_bf16 v[6:9], v[146:149], v[196:199], v[6:9]
	v_mfma_f32_16x16x32_bf16 v[2:5], v[154:157], v[196:199], v[2:5]
	v_mfma_f32_16x16x32_bf16 v[54:57], v[150:153], v[166:169], v[54:57]
	v_mfma_f32_16x16x32_bf16 v[50:53], v[158:161], v[166:169], v[50:53]
	v_mfma_f32_16x16x32_bf16 v[38:41], v[150:153], v[174:177], v[38:41]
	v_mfma_f32_16x16x32_bf16 v[34:37], v[158:161], v[174:177], v[34:37]
	v_mfma_f32_16x16x32_bf16 v[22:25], v[150:153], v[192:195], v[22:25]
	v_mfma_f32_16x16x32_bf16 v[18:21], v[158:161], v[192:195], v[18:21]
	v_mfma_f32_16x16x32_bf16 v[6:9], v[150:153], v[200:203], v[6:9]
	v_mfma_f32_16x16x32_bf16 v[2:5], v[158:161], v[200:203], v[2:5]
	s_barrier
	s_add_i32 s71, 0, 0x18000
	s_add_i32 s80, 0, 0x1c000
	v_add_u32_e32 v142, s71, v224
	v_add_u32_e32 v158, s80, v224
	ds_read_b128 v[130:133], v142
	ds_read_b128 v[134:137], v142 offset:1024
	ds_read_b128 v[138:141], v142 offset:2048
	ds_read_b128 v[142:145], v142 offset:3072
	ds_read_b128 v[146:149], v158
	ds_read_b128 v[150:153], v158 offset:1024
	ds_read_b128 v[154:157], v158 offset:2048
	ds_read_b128 v[158:161], v158 offset:3072
	s_add_u32 s52, s78, 0xb0000
	s_addc_u32 s53, s79, 0
	s_mov_b32 m0, s15
	v_lshl_add_u64 v[230:231], s[52:53], 0, v[182:183]
	ds_read_b128 v[162:165], v226 offset:32768
	ds_read_b128 v[166:169], v226 offset:33792
	ds_read_b128 v[170:173], v226 offset:34816
	ds_read_b128 v[174:177], v226 offset:35840
	ds_read_b128 v[188:191], v226 offset:36864
	ds_read_b128 v[192:195], v226 offset:37888
	ds_read_b128 v[196:199], v226 offset:38912
	ds_read_b128 v[200:203], v226 offset:39936
	global_load_lds_dwordx4 v[230:231], off
	v_lshl_add_u64 v[230:231], s[52:53], 0, v[180:181]
	s_mov_b32 m0, s16
	s_nop 0
	global_load_lds_dwordx4 v[230:231], off
	s_waitcnt vmcnt(8)
	s_waitcnt lgkmcnt(0)
	s_barrier
	s_waitcnt lgkmcnt(0)
	v_mfma_f32_16x16x32_bf16 v[126:129], v[130:133], v[162:165], v[126:129]
	v_mfma_f32_16x16x32_bf16 v[122:125], v[138:141], v[162:165], v[122:125]
	v_mfma_f32_16x16x32_bf16 v[110:113], v[130:133], v[170:173], v[110:113]
	v_mfma_f32_16x16x32_bf16 v[106:109], v[138:141], v[170:173], v[106:109]
	v_mfma_f32_16x16x32_bf16 v[94:97], v[130:133], v[188:191], v[94:97]
	v_mfma_f32_16x16x32_bf16 v[90:93], v[138:141], v[188:191], v[90:93]
	v_mfma_f32_16x16x32_bf16 v[78:81], v[130:133], v[196:199], v[78:81]
	v_mfma_f32_16x16x32_bf16 v[74:77], v[138:141], v[196:199], v[74:77]
	v_mfma_f32_16x16x32_bf16 v[126:129], v[134:137], v[166:169], v[126:129]
	v_mfma_f32_16x16x32_bf16 v[122:125], v[142:145], v[166:169], v[122:125]
	v_mfma_f32_16x16x32_bf16 v[110:113], v[134:137], v[174:177], v[110:113]
	v_mfma_f32_16x16x32_bf16 v[106:109], v[142:145], v[174:177], v[106:109]
	v_mfma_f32_16x16x32_bf16 v[94:97], v[134:137], v[192:195], v[94:97]
	v_mfma_f32_16x16x32_bf16 v[90:93], v[142:145], v[192:195], v[90:93]
	v_mfma_f32_16x16x32_bf16 v[78:81], v[134:137], v[200:203], v[78:81]
	v_mfma_f32_16x16x32_bf16 v[74:77], v[142:145], v[200:203], v[74:77]
	v_mfma_f32_16x16x32_bf16 v[118:121], v[146:149], v[162:165], v[118:121]
	v_mfma_f32_16x16x32_bf16 v[114:117], v[154:157], v[162:165], v[114:117]
	v_mfma_f32_16x16x32_bf16 v[102:105], v[146:149], v[170:173], v[102:105]
	v_mfma_f32_16x16x32_bf16 v[98:101], v[154:157], v[170:173], v[98:101]
	v_mfma_f32_16x16x32_bf16 v[86:89], v[146:149], v[188:191], v[86:89]
	v_mfma_f32_16x16x32_bf16 v[82:85], v[154:157], v[188:191], v[82:85]
	v_mfma_f32_16x16x32_bf16 v[70:73], v[146:149], v[196:199], v[70:73]
	v_mfma_f32_16x16x32_bf16 v[66:69], v[154:157], v[196:199], v[66:69]
	v_mfma_f32_16x16x32_bf16 v[118:121], v[150:153], v[166:169], v[118:121]
	v_mfma_f32_16x16x32_bf16 v[114:117], v[158:161], v[166:169], v[114:117]
	v_mfma_f32_16x16x32_bf16 v[102:105], v[150:153], v[174:177], v[102:105]
	v_mfma_f32_16x16x32_bf16 v[98:101], v[158:161], v[174:177], v[98:101]
	v_mfma_f32_16x16x32_bf16 v[86:89], v[150:153], v[192:195], v[86:89]
	v_mfma_f32_16x16x32_bf16 v[82:85], v[158:161], v[192:195], v[82:85]
	v_mfma_f32_16x16x32_bf16 v[70:73], v[150:153], v[200:203], v[70:73]
	v_mfma_f32_16x16x32_bf16 v[66:69], v[158:161], v[200:203], v[66:69]
	s_barrier
; #define PG8_STAGE(bufoff, gbase, voff) do { _Pragma("unroll") for (int _i = 0; _i < 2; ++_i) \
;         __builtin_amdgcn_global_load_lds((const unsigned*)((const char*)(gbase) + (voff)[_i]), (PG8_LAS unsigned*)(lds + (bufoff) + ldsw + _i * 8192), 16, 0, 0); } while (0)
; #define PG8_LDA(dst, b, h) do { _Pragma("unroll") for (int m = 0; m < 4; ++m) _Pragma("unroll") for (int k = 0; k < 2; ++k) dst[m][k] = *(const PG8_LAS bf16x8*)(lds + PG8_SA(b, h) + aoff + m * 2048 + k * 1024); } while (0)
; #define PG8_MMA(ai, bj, At, Bt) do { __builtin_amdgcn_s_setprio(1); _Pragma("unroll") for (int m = 0; m < 4; ++m) _Pragma("unroll") for (int n = 0; n < 2; ++n) _Pragma("unroll") for (int k = 0; k < 2; ++k) \
;         acc[ai][bj][m][n] = __builtin_amdgcn_mfma_f32_16x16x32_bf16(Bt[n][k], At[m][k], acc[ai][bj][m][n], 0, 0, 0); __builtin_amdgcn_s_setprio(0); } while (0)
; #define PG8_WAIT_V(n) asm volatile("s_waitcnt vmcnt(" #n ")" ::: "memory")
; #define PG8_WAIT_L(n) asm volatile("s_waitcnt lgkmcnt(" #n ")" ::: "memory")
; #define PG8_BAR __builtin_amdgcn_s_barrier()
; #define PG8_SCHED __builtin_amdgcn_sched_barrier(0)
; template <class Epi, class Sched, bool ALIGN_EPI = false>
; __device__ __forceinline__ void gemm_phase(PG8_LAS unsigned char* lds, const Gemm g, const Sched& S, const Epi& E) {
;     ...
;             PG8_LDA(At, 1, 1); PG8_STAGE(PG8_SB(1, 0), b3, voffB); PG8_STAGE(PG8_SB(1, 1), b3 + hstep, voffB); PG8_STAGE(PG8_SA(1, 0), a3, voffA);
;             PG8_WAIT_V(8); PG8_WAIT_L(0); PG8_BAR; PG8_MMA(1, 0, At, B0); PG8_MMA(1, 1, At, B1); PG8_BAR; PG8_SCHED;
;         }
;         if constexpr (ALIGN_EPI) { if (wr == 0) PG8_BAR; }
	s_add_i32 s52, s71, s12
	v_lshl_add_u64 v[204:205], v[204:205], 0, s[34:35]
	s_mov_b32 m0, s52
	ds_read_b128 v[162:165], v226 offset:49152
	ds_read_b128 v[166:169], v226 offset:50176
	ds_read_b128 v[170:173], v226 offset:51200
	ds_read_b128 v[174:177], v226 offset:52224
	ds_read_b128 v[188:191], v226 offset:53248
	ds_read_b128 v[192:195], v226 offset:54272
	ds_read_b128 v[196:199], v226 offset:55296
	ds_read_b128 v[200:203], v226 offset:56320
	global_load_lds_dwordx4 v[204:205], off
	s_add_i32 m0, s52, 0x2000
	s_add_u32 s52, s54, 0xb0080
	v_lshl_add_u64 v[204:205], v[206:207], 0, s[34:35]
	s_addc_u32 s53, s55, 0
	s_add_i32 s54, s80, s12
	global_load_lds_dwordx4 v[204:205], off
	v_lshl_add_u64 v[204:205], s[52:53], 0, v[0:1]
	s_mov_b32 m0, s54
	s_nop 0
	global_load_lds_dwordx4 v[204:205], off
	v_lshl_add_u64 v[204:205], s[52:53], 0, v[178:179]
	s_add_i32 m0, s54, 0x2000
	s_nop 0
	global_load_lds_dwordx4 v[204:205], off
	v_lshl_add_u64 v[204:205], v[208:209], 0, s[34:35]
	s_mov_b32 m0, s17
	s_nop 0
	global_load_lds_dwordx4 v[204:205], off
	v_lshl_add_u64 v[204:205], v[228:229], 0, s[34:35]
	s_mov_b32 m0, s18
	s_nop 0
	global_load_lds_dwordx4 v[204:205], off
	s_waitcnt vmcnt(8)
	s_waitcnt lgkmcnt(0)
	s_barrier
	s_waitcnt lgkmcnt(0)
	v_mfma_f32_16x16x32_bf16 v[62:65], v[130:133], v[162:165], v[62:65]
	v_mfma_f32_16x16x32_bf16 v[58:61], v[138:141], v[162:165], v[58:61]
	v_mfma_f32_16x16x32_bf16 v[46:49], v[130:133], v[170:173], v[46:49]
	v_mfma_f32_16x16x32_bf16 v[42:45], v[138:141], v[170:173], v[42:45]
	v_mfma_f32_16x16x32_bf16 v[30:33], v[130:133], v[188:191], v[30:33]
	v_mfma_f32_16x16x32_bf16 v[26:29], v[138:141], v[188:191], v[26:29]
	v_mfma_f32_16x16x32_bf16 v[14:17], v[130:133], v[196:199], v[14:17]
	v_mfma_f32_16x16x32_bf16 v[10:13], v[138:141], v[196:199], v[10:13]
	v_mfma_f32_16x16x32_bf16 v[62:65], v[134:137], v[166:169], v[62:65]
	v_mfma_f32_16x16x32_bf16 v[58:61], v[142:145], v[166:169], v[58:61]
	v_mfma_f32_16x16x32_bf16 v[46:49], v[134:137], v[174:177], v[46:49]
	v_mfma_f32_16x16x32_bf16 v[42:45], v[142:145], v[174:177], v[42:45]
	v_mfma_f32_16x16x32_bf16 v[30:33], v[134:137], v[192:195], v[30:33]
	v_mfma_f32_16x16x32_bf16 v[26:29], v[142:145], v[192:195], v[26:29]
	v_mfma_f32_16x16x32_bf16 v[14:17], v[134:137], v[200:203], v[14:17]
	v_mfma_f32_16x16x32_bf16 v[10:13], v[142:145], v[200:203], v[10:13]
	v_mfma_f32_16x16x32_bf16 v[54:57], v[146:149], v[162:165], v[54:57]
	v_mfma_f32_16x16x32_bf16 v[50:53], v[154:157], v[162:165], v[50:53]
	v_mfma_f32_16x16x32_bf16 v[38:41], v[146:149], v[170:173], v[38:41]
	v_mfma_f32_16x16x32_bf16 v[34:37], v[154:157], v[170:173], v[34:37]
	v_mfma_f32_16x16x32_bf16 v[22:25], v[146:149], v[188:191], v[22:25]
	v_mfma_f32_16x16x32_bf16 v[18:21], v[154:157], v[188:191], v[18:21]
	v_mfma_f32_16x16x32_bf16 v[6:9], v[146:149], v[196:199], v[6:9]
	v_mfma_f32_16x16x32_bf16 v[2:5], v[154:157], v[196:199], v[2:5]
	v_mfma_f32_16x16x32_bf16 v[54:57], v[150:153], v[166:169], v[54:57]
	v_mfma_f32_16x16x32_bf16 v[50:53], v[158:161], v[166:169], v[50:53]
	v_mfma_f32_16x16x32_bf16 v[38:41], v[150:153], v[174:177], v[38:41]
	v_mfma_f32_16x16x32_bf16 v[34:37], v[158:161], v[174:177], v[34:37]
	v_mfma_f32_16x16x32_bf16 v[22:25], v[150:153], v[192:195], v[22:25]
	v_mfma_f32_16x16x32_bf16 v[18:21], v[158:161], v[192:195], v[18:21]
	v_mfma_f32_16x16x32_bf16 v[6:9], v[150:153], v[200:203], v[6:9]
	v_mfma_f32_16x16x32_bf16 v[2:5], v[158:161], v[200:203], v[2:5]
	s_barrier
	s_add_i32 s5, s5, 2
	s_add_u32 s4, s4, 0x100
	s_addc_u32 s23, s23, 0
	s_cmp_gt_u32 s5, 41
	s_mov_b64 s[52:53], s[76:77]
	s_cbranch_scc0 .LBB0_558
	s_and_b64 vcc, exec, s[30:31]
	s_cbranch_vccz .LBB0_561
	s_barrier

; #define PG8_STAGE(bufoff, gbase, voff) do { _Pragma("unroll") for (int _i = 0; _i < 2; ++_i) \
;         __builtin_amdgcn_global_load_lds((const unsigned*)((const char*)(gbase) + (voff)[_i]), (PG8_LAS unsigned*)(lds + (bufoff) + ldsw + _i * 8192), 16, 0, 0); } while (0)
; #define PG8_LDA(dst, b, h) do { _Pragma("unroll") for (int m = 0; m < 4; ++m) _Pragma("unroll") for (int k = 0; k < 2; ++k) dst[m][k] = *(const PG8_LAS bf16x8*)(lds + PG8_SA(b, h) + aoff + m * 2048 + k * 1024); } while (0)
; #define PG8_LDB(dst, b, h) do { _Pragma("unroll") for (int n = 0; n < 2; ++n) _Pragma("unroll") for (int k = 0; k < 2; ++k) dst[n][k] = *(const PG8_LAS bf16x8*)(lds + PG8_SB(b, h) + boff + n * 2048 + k * 1024); } while (0)
; #define PG8_MMA(ai, bj, At, Bt) do { __builtin_amdgcn_s_setprio(1); _Pragma("unroll") for (int m = 0; m < 4; ++m) _Pragma("unroll") for (int n = 0; n < 2; ++n) _Pragma("unroll") for (int k = 0; k < 2; ++k) \
;         acc[ai][bj][m][n] = __builtin_amdgcn_mfma_f32_16x16x32_bf16(Bt[n][k], At[m][k], acc[ai][bj][m][n], 0, 0, 0); __builtin_amdgcn_s_setprio(0); } while (0)
; #define PG8_WAIT_V(n) asm volatile("s_waitcnt vmcnt(" #n ")" ::: "memory")
; #define PG8_WAIT_L(n) asm volatile("s_waitcnt lgkmcnt(" #n ")" ::: "memory")
; #define PG8_BAR __builtin_amdgcn_s_barrier()
; template <class Epi, class Sched, bool ALIGN_EPI = false>
; __device__ __forceinline__ void gemm_phase(PG8_LAS unsigned char* lds, const Gemm g, const Sched& S, const Epi& E) {
;     ...
;             const bool last = (t == nt - 2);
;             const char* a1 = cA + (size_t)(t + 1) * kstep;
;             const char* a2 = last ? nA : cA + (size_t)(t + 2) * kstep; const char* b2 = last ? nB : cB + (size_t)(t + 2) * kstep;
;             const char* a3 = a2 + kstep; const char* b3 = b2 + kstep;
;             if constexpr (Epi::MID_T > 0) { if (t == Epi::MID_T) E.mid(acc, cur, wr, fr); }
;             PG8_LDB(B0, 0, 0); PG8_LDB(B1, 0, 1); PG8_SCHED; PG8_LDA(At, 0, 0); PG8_STAGE(PG8_SA(1, 1), a1 + hstep, voffA);
;             PG8_WAIT_V(8); PG8_WAIT_L(0); PG8_BAR; PG8_MMA(0, 0, At, B0); PG8_MMA(0, 1, At, B1); PG8_BAR; PG8_SCHED;
;             PG8_LDA(At, 0, 1); PG8_STAGE(PG8_SB(0, 0), b2, voffB); PG8_STAGE(PG8_SB(0, 1), b2 + hstep, voffB); PG8_STAGE(PG8_SA(0, 0), a2, voffA);
;             PG8_WAIT_V(8); PG8_WAIT_L(0); PG8_BAR; PG8_MMA(1, 0, At, B0); PG8_MMA(1, 1, At, B1); PG8_BAR; PG8_SCHED;
.LBB0_605:
	s_add_u32 s5, s48, 0xfffc0080
	s_addc_u32 s26, s49, -1
	s_add_i32 s27, 0, 0x10000
	s_cmp_eq_u32 s4, 12
	s_cselect_b32 s53, s22, s26
	s_cselect_b32 s52, s23, s5
	v_add_u32_e32 v0, s27, v184
	s_cselect_b32 s51, s29, s55
	s_cselect_b32 s50, s43, s54
	s_add_i32 s5, 0, 0x14000
	s_waitcnt vmcnt(0)
	ds_read_b128 v[18:21], v0
	ds_read_b128 v[22:25], v0 offset:1024
	ds_read_b128 v[26:29], v0 offset:2048
	ds_read_b128 v[30:33], v0 offset:3072
	v_add_u32_e32 v0, s5, v184
	ds_read_b128 v[146:149], v0
	ds_read_b128 v[150:153], v0 offset:1024
	ds_read_b128 v[170:173], v0 offset:2048
	ds_read_b128 v[174:177], v0 offset:3072
	v_lshl_add_u64 v[208:209], s[48:49], 0, v[166:167]
	s_add_i32 m0, s8, 0xc000
	ds_read_b128 v[178:181], v186
	ds_read_b128 v[188:191], v186 offset:1024
	ds_read_b128 v[192:195], v186 offset:2048
	ds_read_b128 v[196:199], v186 offset:3072
	ds_read_b128 v[200:203], v186 offset:4096
	ds_read_b128 v[204:207], v186 offset:5120
	ds_read_b128 v[224:227], v186 offset:6144
	ds_read_b128 v[228:231], v186 offset:7168
	global_load_lds_dwordx4 v[208:209], off
	v_lshl_add_u64 v[208:209], s[48:49], 0, v[168:169]
	s_add_i32 m0, s8, 0xe000
	s_nop 0
	global_load_lds_dwordx4 v[208:209], off
	s_waitcnt vmcnt(8)
	s_waitcnt lgkmcnt(0)
	s_barrier
	s_waitcnt lgkmcnt(0)
	v_mfma_f32_16x16x32_bf16 v[142:145], v[18:21], v[178:181], v[142:145]
	v_mfma_f32_16x16x32_bf16 v[138:141], v[26:29], v[178:181], v[138:141]
	v_mfma_f32_16x16x32_bf16 v[126:129], v[18:21], v[192:195], v[126:129]
	v_mfma_f32_16x16x32_bf16 v[122:125], v[26:29], v[192:195], v[122:125]
	v_mfma_f32_16x16x32_bf16 v[110:113], v[18:21], v[200:203], v[110:113]
	v_mfma_f32_16x16x32_bf16 v[106:109], v[26:29], v[200:203], v[106:109]
	v_mfma_f32_16x16x32_bf16 v[94:97], v[18:21], v[224:227], v[94:97]
	v_mfma_f32_16x16x32_bf16 v[90:93], v[26:29], v[224:227], v[90:93]
	v_mfma_f32_16x16x32_bf16 v[142:145], v[22:25], v[188:191], v[142:145]
	v_mfma_f32_16x16x32_bf16 v[138:141], v[30:33], v[188:191], v[138:141]
	v_mfma_f32_16x16x32_bf16 v[126:129], v[22:25], v[196:199], v[126:129]
	v_mfma_f32_16x16x32_bf16 v[122:125], v[30:33], v[196:199], v[122:125]
	v_mfma_f32_16x16x32_bf16 v[110:113], v[22:25], v[204:207], v[110:113]
	v_mfma_f32_16x16x32_bf16 v[106:109], v[30:33], v[204:207], v[106:109]
	v_mfma_f32_16x16x32_bf16 v[94:97], v[22:25], v[228:231], v[94:97]
	v_mfma_f32_16x16x32_bf16 v[90:93], v[30:33], v[228:231], v[90:93]
	v_mfma_f32_16x16x32_bf16 v[134:137], v[146:149], v[178:181], v[134:137]
	v_mfma_f32_16x16x32_bf16 v[130:133], v[170:173], v[178:181], v[130:133]
	v_mfma_f32_16x16x32_bf16 v[118:121], v[146:149], v[192:195], v[118:121]
	v_mfma_f32_16x16x32_bf16 v[114:117], v[170:173], v[192:195], v[114:117]
	v_mfma_f32_16x16x32_bf16 v[102:105], v[146:149], v[200:203], v[102:105]
	v_mfma_f32_16x16x32_bf16 v[98:101], v[170:173], v[200:203], v[98:101]
	v_mfma_f32_16x16x32_bf16 v[86:89], v[146:149], v[224:227], v[86:89]
	v_mfma_f32_16x16x32_bf16 v[82:85], v[170:173], v[224:227], v[82:85]
	v_mfma_f32_16x16x32_bf16 v[134:137], v[150:153], v[188:191], v[134:137]
	v_mfma_f32_16x16x32_bf16 v[130:133], v[174:177], v[188:191], v[130:133]
	v_mfma_f32_16x16x32_bf16 v[118:121], v[150:153], v[196:199], v[118:121]
	v_mfma_f32_16x16x32_bf16 v[114:117], v[174:177], v[196:199], v[114:117]
	v_mfma_f32_16x16x32_bf16 v[102:105], v[150:153], v[204:207], v[102:105]
	v_mfma_f32_16x16x32_bf16 v[98:101], v[174:177], v[204:207], v[98:101]
	v_mfma_f32_16x16x32_bf16 v[86:89], v[150:153], v[228:231], v[86:89]
	v_mfma_f32_16x16x32_bf16 v[82:85], v[174:177], v[228:231], v[82:85]
	s_barrier
	s_add_i32 s26, s27, s36
	v_lshl_add_u64 v[208:209], s[50:51], 0, v[158:159]
	s_mov_b32 m0, s26
	ds_read_b128 v[178:181], v186 offset:16384
	ds_read_b128 v[188:191], v186 offset:17408
	ds_read_b128 v[192:195], v186 offset:18432
	ds_read_b128 v[196:199], v186 offset:19456
	ds_read_b128 v[200:203], v186 offset:20480
	ds_read_b128 v[204:207], v186 offset:21504
	ds_read_b128 v[224:227], v186 offset:22528
	ds_read_b128 v[228:231], v186 offset:23552
	global_load_lds_dwordx4 v[208:209], off
	s_add_i32 m0, s26, 0x2000
	s_add_u32 s82, s50, 0x40000
	v_lshl_add_u64 v[232:233], s[50:51], 0, v[154:155]
	s_addc_u32 s83, s51, 0
	s_add_i32 s5, s5, s36
	global_load_lds_dwordx4 v[232:233], off
	v_lshl_add_u64 v[234:235], s[82:83], 0, v[158:159]
	s_mov_b32 m0, s5
	v_lshl_add_u64 v[236:237], s[52:53], 0, v[156:157]
	global_load_lds_dwordx4 v[234:235], off
	v_lshl_add_u64 v[234:235], s[82:83], 0, v[154:155]
	s_add_i32 m0, s5, 0x2000
	s_nop 0
	global_load_lds_dwordx4 v[234:235], off
	v_lshl_add_u64 v[234:235], s[52:53], 0, v[160:161]
	s_mov_b32 m0, s8
	s_nop 0
	global_load_lds_dwordx4 v[234:235], off
	s_mov_b32 m0, s9
	s_nop 0
	global_load_lds_dwordx4 v[236:237], off
	s_waitcnt vmcnt(8)
	s_waitcnt lgkmcnt(0)
	s_barrier
; #define PG8_STAGE(bufoff, gbase, voff) do { _Pragma("unroll") for (int _i = 0; _i < 2; ++_i) \
;         __builtin_amdgcn_global_load_lds((const unsigned*)((const char*)(gbase) + (voff)[_i]), (PG8_LAS unsigned*)(lds + (bufoff) + ldsw + _i * 8192), 16, 0, 0); } while (0)
; #define PG8_LDA(dst, b, h) do { _Pragma("unroll") for (int m = 0; m < 4; ++m) _Pragma("unroll") for (int k = 0; k < 2; ++k) dst[m][k] = *(const PG8_LAS bf16x8*)(lds + PG8_SA(b, h) + aoff + m * 2048 + k * 1024); } while (0)
; #define PG8_LDB(dst, b, h) do { _Pragma("unroll") for (int n = 0; n < 2; ++n) _Pragma("unroll") for (int k = 0; k < 2; ++k) dst[n][k] = *(const PG8_LAS bf16x8*)(lds + PG8_SB(b, h) + boff + n * 2048 + k * 1024); } while (0)
; #define PG8_MMA(ai, bj, At, Bt) do { __builtin_amdgcn_s_setprio(1); _Pragma("unroll") for (int m = 0; m < 4; ++m) _Pragma("unroll") for (int n = 0; n < 2; ++n) _Pragma("unroll") for (int k = 0; k < 2; ++k) \
;         acc[ai][bj][m][n] = __builtin_amdgcn_mfma_f32_16x16x32_bf16(Bt[n][k], At[m][k], acc[ai][bj][m][n], 0, 0, 0); __builtin_amdgcn_s_setprio(0); } while (0)
; #define PG8_WAIT_V(n) asm volatile("s_waitcnt vmcnt(" #n ")" ::: "memory")
; #define PG8_WAIT_L(n) asm volatile("s_waitcnt lgkmcnt(" #n ")" ::: "memory")
; #define PG8_BAR __builtin_amdgcn_s_barrier()
; #define PG8_SCHED __builtin_amdgcn_sched_barrier(0)
; template <class Epi, class Sched, bool ALIGN_EPI = false>
; __device__ __forceinline__ void gemm_phase(PG8_LAS unsigned char* lds, const Gemm g, const Sched& S, const Epi& E) {
;     ...
;             PG8_WAIT_V(8); PG8_WAIT_L(0); PG8_BAR; PG8_MMA(1, 0, At, B0); PG8_MMA(1, 1, At, B1); PG8_BAR; PG8_SCHED;
;             PG8_LDB(B0, 1, 0); PG8_LDB(B1, 1, 1); PG8_SCHED; PG8_LDA(At, 1, 0); PG8_STAGE(PG8_SA(0, 1), a2 + hstep, voffA);
;             PG8_WAIT_V(8); PG8_WAIT_L(0); PG8_BAR; PG8_MMA(0, 0, At, B0); PG8_MMA(0, 1, At, B1); PG8_BAR; PG8_SCHED;
	s_waitcnt lgkmcnt(0)
	v_mfma_f32_16x16x32_bf16 v[78:81], v[18:21], v[178:181], v[78:81]
	v_mfma_f32_16x16x32_bf16 v[74:77], v[26:29], v[178:181], v[74:77]
	v_mfma_f32_16x16x32_bf16 v[62:65], v[18:21], v[192:195], v[62:65]
	v_mfma_f32_16x16x32_bf16 v[58:61], v[26:29], v[192:195], v[58:61]
	v_mfma_f32_16x16x32_bf16 v[46:49], v[18:21], v[200:203], v[46:49]
	v_mfma_f32_16x16x32_bf16 v[42:45], v[26:29], v[200:203], v[42:45]
	v_mfma_f32_16x16x32_bf16 v[14:17], v[18:21], v[224:227], v[14:17]
	v_mfma_f32_16x16x32_bf16 v[10:13], v[26:29], v[224:227], v[10:13]
	v_mfma_f32_16x16x32_bf16 v[78:81], v[22:25], v[188:191], v[78:81]
	v_mfma_f32_16x16x32_bf16 v[74:77], v[30:33], v[188:191], v[74:77]
	v_mfma_f32_16x16x32_bf16 v[62:65], v[22:25], v[196:199], v[62:65]
	v_mfma_f32_16x16x32_bf16 v[58:61], v[30:33], v[196:199], v[58:61]
	v_mfma_f32_16x16x32_bf16 v[46:49], v[22:25], v[204:207], v[46:49]
	v_mfma_f32_16x16x32_bf16 v[42:45], v[30:33], v[204:207], v[42:45]
	v_mfma_f32_16x16x32_bf16 v[14:17], v[22:25], v[228:231], v[14:17]
	v_mfma_f32_16x16x32_bf16 v[10:13], v[30:33], v[228:231], v[10:13]
	v_mfma_f32_16x16x32_bf16 v[38:41], v[146:149], v[200:203], v[38:41]
	v_mfma_f32_16x16x32_bf16 v[34:37], v[170:173], v[200:203], v[34:37]
	v_mfma_f32_16x16x32_bf16 v[6:9], v[146:149], v[224:227], v[6:9]
	v_mfma_f32_16x16x32_bf16 v[2:5], v[170:173], v[224:227], v[2:5]
	v_mfma_f32_16x16x32_bf16 v[18:21], v[146:149], v[178:181], v[70:73]
	v_mfma_f32_16x16x32_bf16 v[22:25], v[170:173], v[178:181], v[66:69]
	v_mfma_f32_16x16x32_bf16 v[26:29], v[146:149], v[192:195], v[54:57]
	v_mfma_f32_16x16x32_bf16 v[30:33], v[170:173], v[192:195], v[50:53]
	v_mfma_f32_16x16x32_bf16 v[38:41], v[150:153], v[204:207], v[38:41]
	v_mfma_f32_16x16x32_bf16 v[34:37], v[174:177], v[204:207], v[34:37]
	v_mfma_f32_16x16x32_bf16 v[6:9], v[150:153], v[228:231], v[6:9]
	v_mfma_f32_16x16x32_bf16 v[2:5], v[174:177], v[228:231], v[2:5]
	v_mfma_f32_16x16x32_bf16 v[18:21], v[150:153], v[188:191], v[18:21]
	v_mfma_f32_16x16x32_bf16 v[22:25], v[174:177], v[188:191], v[22:25]
	v_mfma_f32_16x16x32_bf16 v[26:29], v[150:153], v[196:199], v[26:29]
	v_mfma_f32_16x16x32_bf16 v[30:33], v[174:177], v[196:199], v[30:33]
	s_barrier
	s_add_i32 s5, 0, 0x18000
	v_add_u32_e32 v0, s5, v184
	s_add_i32 s26, 0, 0x1c000
	ds_read_b128 v[50:53], v0
	ds_read_b128 v[54:57], v0 offset:1024
	ds_read_b128 v[66:69], v0 offset:2048
	ds_read_b128 v[70:73], v0 offset:3072
	v_add_u32_e32 v0, s26, v184
	ds_read_b128 v[146:149], v0
	ds_read_b128 v[150:153], v0 offset:1024
	ds_read_b128 v[170:173], v0 offset:2048
	ds_read_b128 v[174:177], v0 offset:3072
	s_add_u32 s52, s52, 0x40000
	s_addc_u32 s53, s53, 0
	s_mov_b32 m0, s10
	v_lshl_add_u64 v[242:243], s[52:53], 0, v[160:161]
	ds_read_b128 v[178:181], v186 offset:32768
	ds_read_b128 v[188:191], v186 offset:33792
	ds_read_b128 v[192:195], v186 offset:34816
	ds_read_b128 v[196:199], v186 offset:35840
	ds_read_b128 v[200:203], v186 offset:36864
	ds_read_b128 v[204:207], v186 offset:37888
	ds_read_b128 v[224:227], v186 offset:38912
	ds_read_b128 v[228:231], v186 offset:39936
	global_load_lds_dwordx4 v[242:243], off
	v_lshl_add_u64 v[242:243], s[52:53], 0, v[156:157]
	s_mov_b32 m0, s11
	s_nop 0
	global_load_lds_dwordx4 v[242:243], off
	s_waitcnt vmcnt(8)
	s_waitcnt lgkmcnt(0)
	s_barrier
	s_waitcnt lgkmcnt(0)
	v_mfma_f32_16x16x32_bf16 v[142:145], v[50:53], v[178:181], v[142:145]
	v_mfma_f32_16x16x32_bf16 v[138:141], v[66:69], v[178:181], v[138:141]
	v_mfma_f32_16x16x32_bf16 v[126:129], v[50:53], v[192:195], v[126:129]
	v_mfma_f32_16x16x32_bf16 v[122:125], v[66:69], v[192:195], v[122:125]
	v_mfma_f32_16x16x32_bf16 v[110:113], v[50:53], v[200:203], v[110:113]
	v_mfma_f32_16x16x32_bf16 v[106:109], v[66:69], v[200:203], v[106:109]
	v_mfma_f32_16x16x32_bf16 v[94:97], v[50:53], v[224:227], v[94:97]
	v_mfma_f32_16x16x32_bf16 v[90:93], v[66:69], v[224:227], v[90:93]
	v_mfma_f32_16x16x32_bf16 v[142:145], v[54:57], v[188:191], v[142:145]
	v_mfma_f32_16x16x32_bf16 v[138:141], v[70:73], v[188:191], v[138:141]
	v_mfma_f32_16x16x32_bf16 v[126:129], v[54:57], v[196:199], v[126:129]
	v_mfma_f32_16x16x32_bf16 v[122:125], v[70:73], v[196:199], v[122:125]
	v_mfma_f32_16x16x32_bf16 v[110:113], v[54:57], v[204:207], v[110:113]
	v_mfma_f32_16x16x32_bf16 v[106:109], v[70:73], v[204:207], v[106:109]
	v_mfma_f32_16x16x32_bf16 v[94:97], v[54:57], v[228:231], v[94:97]
	v_mfma_f32_16x16x32_bf16 v[90:93], v[70:73], v[228:231], v[90:93]
	v_mfma_f32_16x16x32_bf16 v[134:137], v[146:149], v[178:181], v[134:137]
	v_mfma_f32_16x16x32_bf16 v[130:133], v[170:173], v[178:181], v[130:133]
	v_mfma_f32_16x16x32_bf16 v[118:121], v[146:149], v[192:195], v[118:121]
	v_mfma_f32_16x16x32_bf16 v[114:117], v[170:173], v[192:195], v[114:117]
	v_mfma_f32_16x16x32_bf16 v[102:105], v[146:149], v[200:203], v[102:105]
	v_mfma_f32_16x16x32_bf16 v[98:101], v[170:173], v[200:203], v[98:101]
	v_mfma_f32_16x16x32_bf16 v[86:89], v[146:149], v[224:227], v[86:89]
	v_mfma_f32_16x16x32_bf16 v[82:85], v[170:173], v[224:227], v[82:85]
	v_mfma_f32_16x16x32_bf16 v[134:137], v[150:153], v[188:191], v[134:137]
	v_mfma_f32_16x16x32_bf16 v[130:133], v[174:177], v[188:191], v[130:133]
	v_mfma_f32_16x16x32_bf16 v[118:121], v[150:153], v[196:199], v[118:121]
	v_mfma_f32_16x16x32_bf16 v[114:117], v[174:177], v[196:199], v[114:117]
	v_mfma_f32_16x16x32_bf16 v[102:105], v[150:153], v[204:207], v[102:105]
	v_mfma_f32_16x16x32_bf16 v[98:101], v[174:177], v[204:207], v[98:101]
	v_mfma_f32_16x16x32_bf16 v[86:89], v[150:153], v[228:231], v[86:89]
	v_mfma_f32_16x16x32_bf16 v[82:85], v[174:177], v[228:231], v[82:85]
	s_barrier
; #define PG8_STAGE(bufoff, gbase, voff) do { _Pragma("unroll") for (int _i = 0; _i < 2; ++_i) \
;         __builtin_amdgcn_global_load_lds((const unsigned*)((const char*)(gbase) + (voff)[_i]), (PG8_LAS unsigned*)(lds + (bufoff) + ldsw + _i * 8192), 16, 0, 0); } while (0)
; #define PG8_LDA(dst, b, h) do { _Pragma("unroll") for (int m = 0; m < 4; ++m) _Pragma("unroll") for (int k = 0; k < 2; ++k) dst[m][k] = *(const PG8_LAS bf16x8*)(lds + PG8_SA(b, h) + aoff + m * 2048 + k * 1024); } while (0)
; #define PG8_MMA(ai, bj, At, Bt) do { __builtin_amdgcn_s_setprio(1); _Pragma("unroll") for (int m = 0; m < 4; ++m) _Pragma("unroll") for (int n = 0; n < 2; ++n) _Pragma("unroll") for (int k = 0; k < 2; ++k) \
;         acc[ai][bj][m][n] = __builtin_amdgcn_mfma_f32_16x16x32_bf16(Bt[n][k], At[m][k], acc[ai][bj][m][n], 0, 0, 0); __builtin_amdgcn_s_setprio(0); } while (0)
; #define PG8_WAIT_V(n) asm volatile("s_waitcnt vmcnt(" #n ")" ::: "memory")
; #define PG8_WAIT_L(n) asm volatile("s_waitcnt lgkmcnt(" #n ")" ::: "memory")
; #define PG8_BAR __builtin_amdgcn_s_barrier()
; #define PG8_SCHED __builtin_amdgcn_sched_barrier(0)
; template <class Epi, class Sched, bool ALIGN_EPI = false>
; __device__ __forceinline__ void gemm_phase(PG8_LAS unsigned char* lds, const Gemm g, const Sched& S, const Epi& E) {
;     ...
;             PG8_LDA(At, 1, 1); PG8_STAGE(PG8_SB(1, 0), b3, voffB); PG8_STAGE(PG8_SB(1, 1), b3 + hstep, voffB); PG8_STAGE(PG8_SA(1, 0), a3, voffA);
;             PG8_WAIT_V(8); PG8_WAIT_L(0); PG8_BAR; PG8_MMA(1, 0, At, B0); PG8_MMA(1, 1, At, B1); PG8_BAR; PG8_SCHED;
;         }
;         if constexpr (ALIGN_EPI) { if (wr == 0) PG8_BAR; }
	s_add_i32 s5, s5, s36
	v_lshl_add_u64 v[208:209], v[208:209], 0, s[34:35]
	s_mov_b32 m0, s5
	ds_read_b128 v[178:181], v186 offset:49152
	ds_read_b128 v[188:191], v186 offset:50176
	ds_read_b128 v[192:195], v186 offset:51200
	ds_read_b128 v[196:199], v186 offset:52224
	ds_read_b128 v[200:203], v186 offset:53248
	ds_read_b128 v[204:207], v186 offset:54272
	ds_read_b128 v[224:227], v186 offset:55296
	ds_read_b128 v[228:231], v186 offset:56320
	global_load_lds_dwordx4 v[208:209], off
	s_add_i32 m0, s5, 0x2000
	s_add_u32 s50, s50, 0x40080
	v_lshl_add_u64 v[208:209], v[232:233], 0, s[34:35]
	s_addc_u32 s51, s51, 0
	s_add_i32 s5, s26, s36
	global_load_lds_dwordx4 v[208:209], off
	v_lshl_add_u64 v[208:209], s[50:51], 0, v[158:159]
	s_mov_b32 m0, s5
	s_nop 0
	global_load_lds_dwordx4 v[208:209], off
	v_lshl_add_u64 v[208:209], s[50:51], 0, v[154:155]
	s_add_i32 m0, s5, 0x2000
	s_nop 0
	global_load_lds_dwordx4 v[208:209], off
	v_lshl_add_u64 v[208:209], v[234:235], 0, s[34:35]
	s_mov_b32 m0, s16
	s_nop 0
	global_load_lds_dwordx4 v[208:209], off
	v_lshl_add_u64 v[208:209], v[236:237], 0, s[34:35]
	s_mov_b32 m0, s17
	s_nop 0
	global_load_lds_dwordx4 v[208:209], off
	s_waitcnt vmcnt(8)
	s_waitcnt lgkmcnt(0)
	s_barrier
	s_waitcnt lgkmcnt(0)
	v_mfma_f32_16x16x32_bf16 v[78:81], v[50:53], v[178:181], v[78:81]
	v_mfma_f32_16x16x32_bf16 v[74:77], v[66:69], v[178:181], v[74:77]
	v_mfma_f32_16x16x32_bf16 v[62:65], v[50:53], v[192:195], v[62:65]
	v_mfma_f32_16x16x32_bf16 v[58:61], v[66:69], v[192:195], v[58:61]
	v_mfma_f32_16x16x32_bf16 v[46:49], v[50:53], v[200:203], v[46:49]
	v_mfma_f32_16x16x32_bf16 v[42:45], v[66:69], v[200:203], v[42:45]
	v_mfma_f32_16x16x32_bf16 v[14:17], v[50:53], v[224:227], v[14:17]
	v_mfma_f32_16x16x32_bf16 v[10:13], v[66:69], v[224:227], v[10:13]
	v_mfma_f32_16x16x32_bf16 v[78:81], v[54:57], v[188:191], v[78:81]
	v_mfma_f32_16x16x32_bf16 v[74:77], v[70:73], v[188:191], v[74:77]
	v_mfma_f32_16x16x32_bf16 v[62:65], v[54:57], v[196:199], v[62:65]
	v_mfma_f32_16x16x32_bf16 v[58:61], v[70:73], v[196:199], v[58:61]
	v_mfma_f32_16x16x32_bf16 v[46:49], v[54:57], v[204:207], v[46:49]
	v_mfma_f32_16x16x32_bf16 v[42:45], v[70:73], v[204:207], v[42:45]
	v_mfma_f32_16x16x32_bf16 v[14:17], v[54:57], v[228:231], v[14:17]
	v_mfma_f32_16x16x32_bf16 v[10:13], v[70:73], v[228:231], v[10:13]
	v_mfma_f32_16x16x32_bf16 v[18:21], v[146:149], v[178:181], v[18:21]
	v_mfma_f32_16x16x32_bf16 v[70:73], v[150:153], v[188:191], v[18:21]
	v_mfma_f32_16x16x32_bf16 v[18:21], v[170:173], v[178:181], v[22:25]
	v_mfma_f32_16x16x32_bf16 v[66:69], v[174:177], v[188:191], v[18:21]
	v_mfma_f32_16x16x32_bf16 v[18:21], v[146:149], v[192:195], v[26:29]
	v_mfma_f32_16x16x32_bf16 v[54:57], v[150:153], v[196:199], v[18:21]
	v_mfma_f32_16x16x32_bf16 v[18:21], v[170:173], v[192:195], v[30:33]
	v_mfma_f32_16x16x32_bf16 v[50:53], v[174:177], v[196:199], v[18:21]
	v_mfma_f32_16x16x32_bf16 v[18:21], v[146:149], v[200:203], v[38:41]
	v_mfma_f32_16x16x32_bf16 v[38:41], v[150:153], v[204:207], v[18:21]
	v_mfma_f32_16x16x32_bf16 v[18:21], v[170:173], v[200:203], v[34:37]
	v_mfma_f32_16x16x32_bf16 v[6:9], v[146:149], v[224:227], v[6:9]
	v_mfma_f32_16x16x32_bf16 v[2:5], v[170:173], v[224:227], v[2:5]
	v_mfma_f32_16x16x32_bf16 v[34:37], v[174:177], v[204:207], v[18:21]
	v_mfma_f32_16x16x32_bf16 v[6:9], v[150:153], v[228:231], v[6:9]
	v_mfma_f32_16x16x32_bf16 v[2:5], v[174:177], v[228:231], v[2:5]
	s_barrier
	s_add_i32 s4, s4, 2
	s_add_u32 s48, s48, 0x100
	s_addc_u32 s49, s49, 0
	s_add_u32 s54, s54, 0x100
	s_addc_u32 s55, s55, 0
	s_cmp_gt_u32 s4, 13
	s_cbranch_scc0 .LBB0_605
	s_and_b64 vcc, exec, s[76:77]
	s_cbranch_vccz .LBB0_608
	s_barrier

; #define PG8_STAGE(bufoff, gbase, voff) do { _Pragma("unroll") for (int _i = 0; _i < 2; ++_i) \
;         __builtin_amdgcn_global_load_lds((const unsigned*)((const char*)(gbase) + (voff)[_i]), (PG8_LAS unsigned*)(lds + (bufoff) + ldsw + _i * 8192), 16, 0, 0); } while (0)
; #define PG8_LDA(dst, b, h) do { _Pragma("unroll") for (int m = 0; m < 4; ++m) _Pragma("unroll") for (int k = 0; k < 2; ++k) dst[m][k] = *(const PG8_LAS bf16x8*)(lds + PG8_SA(b, h) + aoff + m * 2048 + k * 1024); } while (0)
; #define PG8_LDB(dst, b, h) do { _Pragma("unroll") for (int n = 0; n < 2; ++n) _Pragma("unroll") for (int k = 0; k < 2; ++k) dst[n][k] = *(const PG8_LAS bf16x8*)(lds + PG8_SB(b, h) + boff + n * 2048 + k * 1024); } while (0)
; #define PG8_MMA(ai, bj, At, Bt) do { __builtin_amdgcn_s_setprio(1); _Pragma("unroll") for (int m = 0; m < 4; ++m) _Pragma("unroll") for (int n = 0; n < 2; ++n) _Pragma("unroll") for (int k = 0; k < 2; ++k) \
;         acc[ai][bj][m][n] = __builtin_amdgcn_mfma_f32_16x16x32_bf16(Bt[n][k], At[m][k], acc[ai][bj][m][n], 0, 0, 0); __builtin_amdgcn_s_setprio(0); } while (0)
; #define PG8_WAIT_V(n) asm volatile("s_waitcnt vmcnt(" #n ")" ::: "memory")
; #define PG8_WAIT_L(n) asm volatile("s_waitcnt lgkmcnt(" #n ")" ::: "memory")
; #define PG8_BAR __builtin_amdgcn_s_barrier()
; template <class Epi, class Sched, bool ALIGN_EPI = false>
; __device__ __forceinline__ void gemm_phase(PG8_LAS unsigned char* lds, const Gemm g, const Sched& S, const Epi& E) {
;     ...
;             const bool last = (t == nt - 2);
;             const char* a1 = cA + (size_t)(t + 1) * kstep;
;             const char* a2 = last ? nA : cA + (size_t)(t + 2) * kstep; const char* b2 = last ? nB : cB + (size_t)(t + 2) * kstep;
;             const char* a3 = a2 + kstep; const char* b3 = b2 + kstep;
;             if constexpr (Epi::MID_T > 0) { if (t == Epi::MID_T) E.mid(acc, cur, wr, fr); }
;             PG8_LDB(B0, 0, 0); PG8_LDB(B1, 0, 1); PG8_SCHED; PG8_LDA(At, 0, 0); PG8_STAGE(PG8_SA(1, 1), a1 + hstep, voffA);
;             PG8_WAIT_V(8); PG8_WAIT_L(0); PG8_BAR; PG8_MMA(0, 0, At, B0); PG8_MMA(0, 1, At, B1); PG8_BAR; PG8_SCHED;
;             PG8_LDA(At, 0, 1); PG8_STAGE(PG8_SB(0, 0), b2, voffB); PG8_STAGE(PG8_SB(0, 1), b2 + hstep, voffB); PG8_STAGE(PG8_SA(0, 0), a2, voffA);
;             PG8_WAIT_V(8); PG8_WAIT_L(0); PG8_BAR; PG8_MMA(1, 0, At, B0); PG8_MMA(1, 1, At, B1); PG8_BAR; PG8_SCHED;
.LBB0_843:
	s_add_u32 s26, s52, 0xfffc0080
	s_addc_u32 s27, s53, -1
	s_add_i32 s40, 0, 0x10000
	s_cmp_eq_u32 s5, 12
	s_cselect_b32 vcc_hi, s21, s27
	s_cselect_b32 vcc_lo, s36, s26
	v_add_u32_e32 v0, s40, v151
	s_cselect_b32 s55, s93, s4
	s_cselect_b32 s54, s95, s71
	s_add_i32 s41, 0, 0x14000
	ds_read_b128 v[122:125], v0
	ds_read_b128 v[126:129], v0 offset:1024
	ds_read_b128 v[162:165], v0 offset:2048
	ds_read_b128 v[166:169], v0 offset:3072
	v_add_u32_e32 v0, s41, v151
	ds_read_b128 v[170:173], v0
	ds_read_b128 v[174:177], v0 offset:1024
	ds_read_b128 v[178:181], v0 offset:2048
	ds_read_b128 v[182:185], v0 offset:3072
	v_lshl_add_u64 v[228:229], s[52:53], 0, v[158:159]
	s_add_i32 m0, s11, 0xc000
	ds_read_b128 v[186:189], v230
	ds_read_b128 v[190:193], v230 offset:1024
	ds_read_b128 v[194:197], v230 offset:2048
	ds_read_b128 v[198:201], v230 offset:3072
	ds_read_b128 v[202:205], v230 offset:4096
	ds_read_b128 v[206:209], v230 offset:5120
	ds_read_b128 v[224:227], v230 offset:6144
	ds_read_b128 v[232:235], v230 offset:7168
	global_load_lds_dwordx4 v[228:229], off
	v_lshl_add_u64 v[228:229], s[52:53], 0, v[160:161]
	s_add_i32 m0, s11, 0xe000
	s_nop 0
	global_load_lds_dwordx4 v[228:229], off
	s_waitcnt vmcnt(8)
	s_waitcnt lgkmcnt(0)
	s_barrier
	s_waitcnt lgkmcnt(0)
	v_mfma_f32_16x16x32_bf16 v[134:137], v[122:125], v[186:189], v[134:137]
	v_mfma_f32_16x16x32_bf16 v[130:133], v[162:165], v[186:189], v[130:133]
	v_mfma_f32_16x16x32_bf16 v[118:121], v[122:125], v[194:197], v[118:121]
	v_mfma_f32_16x16x32_bf16 v[114:117], v[162:165], v[194:197], v[114:117]
	v_mfma_f32_16x16x32_bf16 v[110:113], v[122:125], v[202:205], v[110:113]
	v_mfma_f32_16x16x32_bf16 v[106:109], v[162:165], v[202:205], v[106:109]
	v_mfma_f32_16x16x32_bf16 v[102:105], v[122:125], v[224:227], v[102:105]
	v_mfma_f32_16x16x32_bf16 v[98:101], v[162:165], v[224:227], v[98:101]
	v_mfma_f32_16x16x32_bf16 v[134:137], v[126:129], v[190:193], v[134:137]
	v_mfma_f32_16x16x32_bf16 v[130:133], v[166:169], v[190:193], v[130:133]
	v_mfma_f32_16x16x32_bf16 v[118:121], v[126:129], v[198:201], v[118:121]
	v_mfma_f32_16x16x32_bf16 v[114:117], v[166:169], v[198:201], v[114:117]
	v_mfma_f32_16x16x32_bf16 v[110:113], v[126:129], v[206:209], v[110:113]
	v_mfma_f32_16x16x32_bf16 v[106:109], v[166:169], v[206:209], v[106:109]
	v_mfma_f32_16x16x32_bf16 v[102:105], v[126:129], v[232:235], v[102:105]
	v_mfma_f32_16x16x32_bf16 v[98:101], v[166:169], v[232:235], v[98:101]
	v_mfma_f32_16x16x32_bf16 v[62:65], v[170:173], v[186:189], v[62:65]
	v_mfma_f32_16x16x32_bf16 v[58:61], v[178:181], v[186:189], v[58:61]
	v_mfma_f32_16x16x32_bf16 v[54:57], v[170:173], v[194:197], v[54:57]
	v_mfma_f32_16x16x32_bf16 v[50:53], v[178:181], v[194:197], v[50:53]
	v_mfma_f32_16x16x32_bf16 v[46:49], v[170:173], v[202:205], v[46:49]
	v_mfma_f32_16x16x32_bf16 v[42:45], v[178:181], v[202:205], v[42:45]
	v_mfma_f32_16x16x32_bf16 v[38:41], v[170:173], v[224:227], v[38:41]
	v_mfma_f32_16x16x32_bf16 v[34:37], v[178:181], v[224:227], v[34:37]
	v_mfma_f32_16x16x32_bf16 v[62:65], v[174:177], v[190:193], v[62:65]
	v_mfma_f32_16x16x32_bf16 v[58:61], v[182:185], v[190:193], v[58:61]
	v_mfma_f32_16x16x32_bf16 v[54:57], v[174:177], v[198:201], v[54:57]
	v_mfma_f32_16x16x32_bf16 v[50:53], v[182:185], v[198:201], v[50:53]
	v_mfma_f32_16x16x32_bf16 v[46:49], v[174:177], v[206:209], v[46:49]
	v_mfma_f32_16x16x32_bf16 v[42:45], v[182:185], v[206:209], v[42:45]
	v_mfma_f32_16x16x32_bf16 v[38:41], v[174:177], v[232:235], v[38:41]
	v_mfma_f32_16x16x32_bf16 v[34:37], v[182:185], v[232:235], v[34:37]
	s_barrier
	s_add_i32 s26, s40, s6
	v_lshl_add_u64 v[228:229], s[54:55], 0, v[142:143]
	s_mov_b32 m0, s26
	ds_read_b128 v[186:189], v230 offset:16384
	ds_read_b128 v[190:193], v230 offset:17408
	ds_read_b128 v[194:197], v230 offset:18432
	ds_read_b128 v[198:201], v230 offset:19456
	ds_read_b128 v[202:205], v230 offset:20480
	ds_read_b128 v[206:209], v230 offset:21504
	ds_read_b128 v[224:227], v230 offset:22528
	ds_read_b128 v[232:235], v230 offset:23552
	global_load_lds_dwordx4 v[228:229], off
	s_add_i32 m0, s26, 0x2000
	s_add_u32 s26, s54, 0x40000
	v_lshl_add_u64 v[236:237], s[54:55], 0, v[138:139]
	s_addc_u32 s27, s55, 0
	s_add_i32 s40, s41, s6
	global_load_lds_dwordx4 v[236:237], off
	v_lshl_add_u64 v[242:243], s[26:27], 0, v[142:143]
	s_mov_b32 m0, s40
	v_lshl_add_u64 v[244:245], vcc, 0, v[140:141]
	global_load_lds_dwordx4 v[242:243], off
	v_lshl_add_u64 v[242:243], s[26:27], 0, v[138:139]
	s_add_i32 m0, s40, 0x2000
	s_nop 0
	global_load_lds_dwordx4 v[242:243], off
	v_lshl_add_u64 v[242:243], vcc, 0, v[144:145]
	s_mov_b32 m0, s11
	s_nop 0
	global_load_lds_dwordx4 v[242:243], off
	s_mov_b32 m0, s12
	s_nop 0
	global_load_lds_dwordx4 v[244:245], off
	s_waitcnt vmcnt(8)
	s_waitcnt lgkmcnt(0)
	s_barrier
; #define PG8_STAGE(bufoff, gbase, voff) do { _Pragma("unroll") for (int _i = 0; _i < 2; ++_i) \
;         __builtin_amdgcn_global_load_lds((const unsigned*)((const char*)(gbase) + (voff)[_i]), (PG8_LAS unsigned*)(lds + (bufoff) + ldsw + _i * 8192), 16, 0, 0); } while (0)
; #define PG8_LDA(dst, b, h) do { _Pragma("unroll") for (int m = 0; m < 4; ++m) _Pragma("unroll") for (int k = 0; k < 2; ++k) dst[m][k] = *(const PG8_LAS bf16x8*)(lds + PG8_SA(b, h) + aoff + m * 2048 + k * 1024); } while (0)
; #define PG8_LDB(dst, b, h) do { _Pragma("unroll") for (int n = 0; n < 2; ++n) _Pragma("unroll") for (int k = 0; k < 2; ++k) dst[n][k] = *(const PG8_LAS bf16x8*)(lds + PG8_SB(b, h) + boff + n * 2048 + k * 1024); } while (0)
; #define PG8_MMA(ai, bj, At, Bt) do { __builtin_amdgcn_s_setprio(1); _Pragma("unroll") for (int m = 0; m < 4; ++m) _Pragma("unroll") for (int n = 0; n < 2; ++n) _Pragma("unroll") for (int k = 0; k < 2; ++k) \
;         acc[ai][bj][m][n] = __builtin_amdgcn_mfma_f32_16x16x32_bf16(Bt[n][k], At[m][k], acc[ai][bj][m][n], 0, 0, 0); __builtin_amdgcn_s_setprio(0); } while (0)
; #define PG8_WAIT_V(n) asm volatile("s_waitcnt vmcnt(" #n ")" ::: "memory")
; #define PG8_WAIT_L(n) asm volatile("s_waitcnt lgkmcnt(" #n ")" ::: "memory")
; #define PG8_BAR __builtin_amdgcn_s_barrier()
; #define PG8_SCHED __builtin_amdgcn_sched_barrier(0)
; template <class Epi, class Sched, bool ALIGN_EPI = false>
; __device__ __forceinline__ void gemm_phase(PG8_LAS unsigned char* lds, const Gemm g, const Sched& S, const Epi& E) {
;     ...
;             PG8_WAIT_V(8); PG8_WAIT_L(0); PG8_BAR; PG8_MMA(1, 0, At, B0); PG8_MMA(1, 1, At, B1); PG8_BAR; PG8_SCHED;
;             PG8_LDB(B0, 1, 0); PG8_LDB(B1, 1, 1); PG8_SCHED; PG8_LDA(At, 1, 0); PG8_STAGE(PG8_SA(0, 1), a2 + hstep, voffA);
;             PG8_WAIT_V(8); PG8_WAIT_L(0); PG8_BAR; PG8_MMA(0, 0, At, B0); PG8_MMA(0, 1, At, B1); PG8_BAR; PG8_SCHED;
	s_waitcnt lgkmcnt(0)
	v_mfma_f32_16x16x32_bf16 v[94:97], v[122:125], v[186:189], v[94:97]
	v_mfma_f32_16x16x32_bf16 v[90:93], v[162:165], v[186:189], v[90:93]
	v_mfma_f32_16x16x32_bf16 v[86:89], v[122:125], v[194:197], v[86:89]
	v_mfma_f32_16x16x32_bf16 v[82:85], v[162:165], v[194:197], v[82:85]
	v_mfma_f32_16x16x32_bf16 v[78:81], v[122:125], v[202:205], v[78:81]
	v_mfma_f32_16x16x32_bf16 v[74:77], v[162:165], v[202:205], v[74:77]
	v_mfma_f32_16x16x32_bf16 v[70:73], v[122:125], v[224:227], v[70:73]
	v_mfma_f32_16x16x32_bf16 v[66:69], v[162:165], v[224:227], v[66:69]
	v_mfma_f32_16x16x32_bf16 v[94:97], v[126:129], v[190:193], v[94:97]
	v_mfma_f32_16x16x32_bf16 v[90:93], v[166:169], v[190:193], v[90:93]
	v_mfma_f32_16x16x32_bf16 v[86:89], v[126:129], v[198:201], v[86:89]
	v_mfma_f32_16x16x32_bf16 v[82:85], v[166:169], v[198:201], v[82:85]
	v_mfma_f32_16x16x32_bf16 v[78:81], v[126:129], v[206:209], v[78:81]
	v_mfma_f32_16x16x32_bf16 v[74:77], v[166:169], v[206:209], v[74:77]
	v_mfma_f32_16x16x32_bf16 v[70:73], v[126:129], v[232:235], v[70:73]
	v_mfma_f32_16x16x32_bf16 v[66:69], v[166:169], v[232:235], v[66:69]
	v_mfma_f32_16x16x32_bf16 v[30:33], v[170:173], v[186:189], v[30:33]
	v_mfma_f32_16x16x32_bf16 v[26:29], v[178:181], v[186:189], v[26:29]
	v_mfma_f32_16x16x32_bf16 v[22:25], v[170:173], v[194:197], v[22:25]
	v_mfma_f32_16x16x32_bf16 v[18:21], v[178:181], v[194:197], v[18:21]
	v_mfma_f32_16x16x32_bf16 v[14:17], v[170:173], v[202:205], v[14:17]
	v_mfma_f32_16x16x32_bf16 v[10:13], v[178:181], v[202:205], v[10:13]
	v_mfma_f32_16x16x32_bf16 v[6:9], v[170:173], v[224:227], v[6:9]
	v_mfma_f32_16x16x32_bf16 v[2:5], v[178:181], v[224:227], v[2:5]
	v_mfma_f32_16x16x32_bf16 v[30:33], v[174:177], v[190:193], v[30:33]
	v_mfma_f32_16x16x32_bf16 v[26:29], v[182:185], v[190:193], v[26:29]
	v_mfma_f32_16x16x32_bf16 v[22:25], v[174:177], v[198:201], v[22:25]
	v_mfma_f32_16x16x32_bf16 v[18:21], v[182:185], v[198:201], v[18:21]
	v_mfma_f32_16x16x32_bf16 v[14:17], v[174:177], v[206:209], v[14:17]
	v_mfma_f32_16x16x32_bf16 v[10:13], v[182:185], v[206:209], v[10:13]
	v_mfma_f32_16x16x32_bf16 v[6:9], v[174:177], v[232:235], v[6:9]
	v_mfma_f32_16x16x32_bf16 v[2:5], v[182:185], v[232:235], v[2:5]
	s_barrier
	s_add_i32 s40, 0, 0x18000
	v_add_u32_e32 v0, s40, v151
	s_add_i32 s41, 0, 0x1c000
	ds_read_b128 v[122:125], v0
	ds_read_b128 v[126:129], v0 offset:1024
	ds_read_b128 v[162:165], v0 offset:2048
	ds_read_b128 v[166:169], v0 offset:3072
	v_add_u32_e32 v0, s41, v151
	ds_read_b128 v[170:173], v0
	ds_read_b128 v[174:177], v0 offset:1024
	ds_read_b128 v[178:181], v0 offset:2048
	ds_read_b128 v[182:185], v0 offset:3072
	s_add_u32 s26, vcc_lo, 0x40000
	s_addc_u32 s27, vcc_hi, 0
	s_mov_b32 m0, s13
	v_lshl_add_u64 v[246:247], s[26:27], 0, v[144:145]
	ds_read_b128 v[186:189], v230 offset:32768
	ds_read_b128 v[190:193], v230 offset:33792
	ds_read_b128 v[194:197], v230 offset:34816
	ds_read_b128 v[198:201], v230 offset:35840
	ds_read_b128 v[202:205], v230 offset:36864
	ds_read_b128 v[206:209], v230 offset:37888
	ds_read_b128 v[224:227], v230 offset:38912
	ds_read_b128 v[232:235], v230 offset:39936
	global_load_lds_dwordx4 v[246:247], off
	v_lshl_add_u64 v[246:247], s[26:27], 0, v[140:141]
	s_mov_b32 m0, s14
	s_nop 0
	global_load_lds_dwordx4 v[246:247], off
	s_waitcnt vmcnt(8)
	s_waitcnt lgkmcnt(0)
	s_barrier
	s_waitcnt lgkmcnt(0)
	v_mfma_f32_16x16x32_bf16 v[134:137], v[122:125], v[186:189], v[134:137]
	v_mfma_f32_16x16x32_bf16 v[130:133], v[162:165], v[186:189], v[130:133]
	v_mfma_f32_16x16x32_bf16 v[118:121], v[122:125], v[194:197], v[118:121]
	v_mfma_f32_16x16x32_bf16 v[114:117], v[162:165], v[194:197], v[114:117]
	v_mfma_f32_16x16x32_bf16 v[110:113], v[122:125], v[202:205], v[110:113]
	v_mfma_f32_16x16x32_bf16 v[106:109], v[162:165], v[202:205], v[106:109]
	v_mfma_f32_16x16x32_bf16 v[102:105], v[122:125], v[224:227], v[102:105]
	v_mfma_f32_16x16x32_bf16 v[98:101], v[162:165], v[224:227], v[98:101]
	v_mfma_f32_16x16x32_bf16 v[134:137], v[126:129], v[190:193], v[134:137]
	v_mfma_f32_16x16x32_bf16 v[130:133], v[166:169], v[190:193], v[130:133]
	v_mfma_f32_16x16x32_bf16 v[118:121], v[126:129], v[198:201], v[118:121]
	v_mfma_f32_16x16x32_bf16 v[114:117], v[166:169], v[198:201], v[114:117]
	v_mfma_f32_16x16x32_bf16 v[110:113], v[126:129], v[206:209], v[110:113]
	v_mfma_f32_16x16x32_bf16 v[106:109], v[166:169], v[206:209], v[106:109]
	v_mfma_f32_16x16x32_bf16 v[102:105], v[126:129], v[232:235], v[102:105]
	v_mfma_f32_16x16x32_bf16 v[98:101], v[166:169], v[232:235], v[98:101]
	v_mfma_f32_16x16x32_bf16 v[62:65], v[170:173], v[186:189], v[62:65]
	v_mfma_f32_16x16x32_bf16 v[58:61], v[178:181], v[186:189], v[58:61]
	v_mfma_f32_16x16x32_bf16 v[54:57], v[170:173], v[194:197], v[54:57]
	v_mfma_f32_16x16x32_bf16 v[50:53], v[178:181], v[194:197], v[50:53]
	v_mfma_f32_16x16x32_bf16 v[46:49], v[170:173], v[202:205], v[46:49]
	v_mfma_f32_16x16x32_bf16 v[42:45], v[178:181], v[202:205], v[42:45]
	v_mfma_f32_16x16x32_bf16 v[38:41], v[170:173], v[224:227], v[38:41]
	v_mfma_f32_16x16x32_bf16 v[34:37], v[178:181], v[224:227], v[34:37]
	v_mfma_f32_16x16x32_bf16 v[62:65], v[174:177], v[190:193], v[62:65]
	v_mfma_f32_16x16x32_bf16 v[58:61], v[182:185], v[190:193], v[58:61]
	v_mfma_f32_16x16x32_bf16 v[54:57], v[174:177], v[198:201], v[54:57]
	v_mfma_f32_16x16x32_bf16 v[50:53], v[182:185], v[198:201], v[50:53]
	v_mfma_f32_16x16x32_bf16 v[46:49], v[174:177], v[206:209], v[46:49]
	v_mfma_f32_16x16x32_bf16 v[42:45], v[182:185], v[206:209], v[42:45]
	v_mfma_f32_16x16x32_bf16 v[38:41], v[174:177], v[232:235], v[38:41]
	v_mfma_f32_16x16x32_bf16 v[34:37], v[182:185], v[232:235], v[34:37]
	s_barrier
; #define PG8_STAGE(bufoff, gbase, voff) do { _Pragma("unroll") for (int _i = 0; _i < 2; ++_i) \
;         __builtin_amdgcn_global_load_lds((const unsigned*)((const char*)(gbase) + (voff)[_i]), (PG8_LAS unsigned*)(lds + (bufoff) + ldsw + _i * 8192), 16, 0, 0); } while (0)
; #define PG8_LDA(dst, b, h) do { _Pragma("unroll") for (int m = 0; m < 4; ++m) _Pragma("unroll") for (int k = 0; k < 2; ++k) dst[m][k] = *(const PG8_LAS bf16x8*)(lds + PG8_SA(b, h) + aoff + m * 2048 + k * 1024); } while (0)
; #define PG8_MMA(ai, bj, At, Bt) do { __builtin_amdgcn_s_setprio(1); _Pragma("unroll") for (int m = 0; m < 4; ++m) _Pragma("unroll") for (int n = 0; n < 2; ++n) _Pragma("unroll") for (int k = 0; k < 2; ++k) \
;         acc[ai][bj][m][n] = __builtin_amdgcn_mfma_f32_16x16x32_bf16(Bt[n][k], At[m][k], acc[ai][bj][m][n], 0, 0, 0); __builtin_amdgcn_s_setprio(0); } while (0)
; #define PG8_WAIT_V(n) asm volatile("s_waitcnt vmcnt(" #n ")" ::: "memory")
; #define PG8_WAIT_L(n) asm volatile("s_waitcnt lgkmcnt(" #n ")" ::: "memory")
; #define PG8_BAR __builtin_amdgcn_s_barrier()
; #define PG8_SCHED __builtin_amdgcn_sched_barrier(0)
; template <class Epi, class Sched, bool ALIGN_EPI = false>
; __device__ __forceinline__ void gemm_phase(PG8_LAS unsigned char* lds, const Gemm g, const Sched& S, const Epi& E) {
;     ...
;             PG8_LDA(At, 1, 1); PG8_STAGE(PG8_SB(1, 0), b3, voffB); PG8_STAGE(PG8_SB(1, 1), b3 + hstep, voffB); PG8_STAGE(PG8_SA(1, 0), a3, voffA);
;             PG8_WAIT_V(8); PG8_WAIT_L(0); PG8_BAR; PG8_MMA(1, 0, At, B0); PG8_MMA(1, 1, At, B1); PG8_BAR; PG8_SCHED;
;         }
;         if constexpr (ALIGN_EPI) { if (wr == 0) PG8_BAR; }
	s_add_i32 s26, s40, s6
	v_lshl_add_u64 v[228:229], v[228:229], 0, s[34:35]
	s_mov_b32 m0, s26
	ds_read_b128 v[186:189], v230 offset:49152
	ds_read_b128 v[190:193], v230 offset:50176
	ds_read_b128 v[194:197], v230 offset:51200
	ds_read_b128 v[198:201], v230 offset:52224
	ds_read_b128 v[202:205], v230 offset:53248
	ds_read_b128 v[206:209], v230 offset:54272
	ds_read_b128 v[224:227], v230 offset:55296
	ds_read_b128 v[232:235], v230 offset:56320
	global_load_lds_dwordx4 v[228:229], off
	s_add_i32 m0, s26, 0x2000
	s_add_u32 s26, s54, 0x40080
	v_lshl_add_u64 v[228:229], v[236:237], 0, s[34:35]
	s_addc_u32 s27, s55, 0
	s_add_i32 s40, s41, s6
	global_load_lds_dwordx4 v[228:229], off
	v_lshl_add_u64 v[228:229], s[26:27], 0, v[142:143]
	s_mov_b32 m0, s40
	s_nop 0
	global_load_lds_dwordx4 v[228:229], off
	v_lshl_add_u64 v[228:229], s[26:27], 0, v[138:139]
	s_add_i32 m0, s40, 0x2000
	s_nop 0
	global_load_lds_dwordx4 v[228:229], off
	v_lshl_add_u64 v[228:229], v[242:243], 0, s[34:35]
	s_mov_b32 m0, s17
	s_nop 0
	global_load_lds_dwordx4 v[228:229], off
	v_lshl_add_u64 v[228:229], v[244:245], 0, s[34:35]
	s_mov_b32 m0, s18
	s_nop 0
	global_load_lds_dwordx4 v[228:229], off
	s_waitcnt vmcnt(8)
	s_waitcnt lgkmcnt(0)
	s_barrier
	s_waitcnt lgkmcnt(0)
	v_mfma_f32_16x16x32_bf16 v[94:97], v[122:125], v[186:189], v[94:97]
	v_mfma_f32_16x16x32_bf16 v[90:93], v[162:165], v[186:189], v[90:93]
	v_mfma_f32_16x16x32_bf16 v[86:89], v[122:125], v[194:197], v[86:89]
	v_mfma_f32_16x16x32_bf16 v[82:85], v[162:165], v[194:197], v[82:85]
	v_mfma_f32_16x16x32_bf16 v[78:81], v[122:125], v[202:205], v[78:81]
	v_mfma_f32_16x16x32_bf16 v[74:77], v[162:165], v[202:205], v[74:77]
	v_mfma_f32_16x16x32_bf16 v[70:73], v[122:125], v[224:227], v[70:73]
	v_mfma_f32_16x16x32_bf16 v[66:69], v[162:165], v[224:227], v[66:69]
	v_mfma_f32_16x16x32_bf16 v[94:97], v[126:129], v[190:193], v[94:97]
	v_mfma_f32_16x16x32_bf16 v[90:93], v[166:169], v[190:193], v[90:93]
	v_mfma_f32_16x16x32_bf16 v[86:89], v[126:129], v[198:201], v[86:89]
	v_mfma_f32_16x16x32_bf16 v[82:85], v[166:169], v[198:201], v[82:85]
	v_mfma_f32_16x16x32_bf16 v[78:81], v[126:129], v[206:209], v[78:81]
	v_mfma_f32_16x16x32_bf16 v[74:77], v[166:169], v[206:209], v[74:77]
	v_mfma_f32_16x16x32_bf16 v[70:73], v[126:129], v[232:235], v[70:73]
	v_mfma_f32_16x16x32_bf16 v[66:69], v[166:169], v[232:235], v[66:69]
	v_mfma_f32_16x16x32_bf16 v[30:33], v[170:173], v[186:189], v[30:33]
	v_mfma_f32_16x16x32_bf16 v[26:29], v[178:181], v[186:189], v[26:29]
	v_mfma_f32_16x16x32_bf16 v[22:25], v[170:173], v[194:197], v[22:25]
	v_mfma_f32_16x16x32_bf16 v[18:21], v[178:181], v[194:197], v[18:21]
	v_mfma_f32_16x16x32_bf16 v[14:17], v[170:173], v[202:205], v[14:17]
	v_mfma_f32_16x16x32_bf16 v[10:13], v[178:181], v[202:205], v[10:13]
	v_mfma_f32_16x16x32_bf16 v[6:9], v[170:173], v[224:227], v[6:9]
	v_mfma_f32_16x16x32_bf16 v[2:5], v[178:181], v[224:227], v[2:5]
	v_mfma_f32_16x16x32_bf16 v[30:33], v[174:177], v[190:193], v[30:33]
	v_mfma_f32_16x16x32_bf16 v[26:29], v[182:185], v[190:193], v[26:29]
	v_mfma_f32_16x16x32_bf16 v[22:25], v[174:177], v[198:201], v[22:25]
	v_mfma_f32_16x16x32_bf16 v[18:21], v[182:185], v[198:201], v[18:21]
	v_mfma_f32_16x16x32_bf16 v[14:17], v[174:177], v[206:209], v[14:17]
	v_mfma_f32_16x16x32_bf16 v[10:13], v[182:185], v[206:209], v[10:13]
	v_mfma_f32_16x16x32_bf16 v[6:9], v[174:177], v[232:235], v[6:9]
	v_mfma_f32_16x16x32_bf16 v[2:5], v[182:185], v[232:235], v[2:5]
	s_barrier
	s_add_i32 s5, s5, 2
	s_add_u32 s52, s52, 0x100
	s_addc_u32 s53, s53, 0
	s_add_u32 s71, s71, 0x100
	s_addc_u32 s4, s4, 0
	s_cmp_gt_u32 s5, 13
	s_cbranch_scc0 .LBB0_843
	s_and_b64 vcc, exec, s[90:91]
	s_cbranch_vccz .LBB0_846
	s_barrier

; #define PG8_STAGE(bufoff, gbase, voff) do { _Pragma("unroll") for (int _i = 0; _i < 2; ++_i) \
;         __builtin_amdgcn_global_load_lds((const unsigned*)((const char*)(gbase) + (voff)[_i]), (PG8_LAS unsigned*)(lds + (bufoff) + ldsw + _i * 8192), 16, 0, 0); } while (0)
; #define PG8_LDA(dst, b, h) do { _Pragma("unroll") for (int m = 0; m < 4; ++m) _Pragma("unroll") for (int k = 0; k < 2; ++k) dst[m][k] = *(const PG8_LAS bf16x8*)(lds + PG8_SA(b, h) + aoff + m * 2048 + k * 1024); } while (0)
; #define PG8_LDB(dst, b, h) do { _Pragma("unroll") for (int n = 0; n < 2; ++n) _Pragma("unroll") for (int k = 0; k < 2; ++k) dst[n][k] = *(const PG8_LAS bf16x8*)(lds + PG8_SB(b, h) + boff + n * 2048 + k * 1024); } while (0)
; #define PG8_MMA(ai, bj, At, Bt) do { __builtin_amdgcn_s_setprio(1); _Pragma("unroll") for (int m = 0; m < 4; ++m) _Pragma("unroll") for (int n = 0; n < 2; ++n) _Pragma("unroll") for (int k = 0; k < 2; ++k) \
;         acc[ai][bj][m][n] = __builtin_amdgcn_mfma_f32_16x16x32_bf16(Bt[n][k], At[m][k], acc[ai][bj][m][n], 0, 0, 0); __builtin_amdgcn_s_setprio(0); } while (0)
; #define PG8_WAIT_V(n) asm volatile("s_waitcnt vmcnt(" #n ")" ::: "memory")
; #define PG8_WAIT_L(n) asm volatile("s_waitcnt lgkmcnt(" #n ")" ::: "memory")
; #define PG8_BAR __builtin_amdgcn_s_barrier()
; template <class Epi, class Sched, bool ALIGN_EPI = false>
; __device__ __forceinline__ void gemm_phase(PG8_LAS unsigned char* lds, const Gemm g, const Sched& S, const Epi& E) {
;     ...
;             const bool last = (t == nt - 2);
;             const char* a1 = cA + (size_t)(t + 1) * kstep;
;             const char* a2 = last ? nA : cA + (size_t)(t + 2) * kstep; const char* b2 = last ? nB : cB + (size_t)(t + 2) * kstep;
;             const char* a3 = a2 + kstep; const char* b3 = b2 + kstep;
;             if constexpr (Epi::MID_T > 0) { if (t == Epi::MID_T) E.mid(acc, cur, wr, fr); }
;             PG8_LDB(B0, 0, 0); PG8_LDB(B1, 0, 1); PG8_SCHED; PG8_LDA(At, 0, 0); PG8_STAGE(PG8_SA(1, 1), a1 + hstep, voffA);
;             PG8_WAIT_V(8); PG8_WAIT_L(0); PG8_BAR; PG8_MMA(0, 0, At, B0); PG8_MMA(0, 1, At, B1); PG8_BAR; PG8_SCHED;
;             PG8_LDA(At, 0, 1); PG8_STAGE(PG8_SB(0, 0), b2, voffB); PG8_STAGE(PG8_SB(0, 1), b2 + hstep, voffB); PG8_STAGE(PG8_SA(0, 0), a2, voffA);
;             PG8_WAIT_V(8); PG8_WAIT_L(0); PG8_BAR; PG8_MMA(1, 0, At, B0); PG8_MMA(1, 1, At, B1); PG8_BAR; PG8_SCHED;
.LBB0_1199:
	s_add_u32 s4, s82, s88
	s_addc_u32 s5, s83, s89
	s_add_u32 s4, s4, 0x100
	s_addc_u32 s5, s5, 0
	s_add_u32 s22, s53, s88
	s_addc_u32 s23, s77, s89
	s_cmpk_eq_i32 s88, 0x700
	s_cselect_b32 s91, s19, s5
	s_cselect_b32 s90, s20, s4
	s_cselect_b32 s55, s21, s23
	s_cselect_b32 s54, s36, s22
	s_add_i32 s4, 0, 0x10000
	v_add_u32_e32 v0, s4, v209
	s_add_i32 s22, 0, 0x14000
	ds_read_b128 v[138:141], v0
	ds_read_b128 v[142:145], v0 offset:1024
	ds_read_b128 v[146:149], v0 offset:2048
	ds_read_b128 v[150:153], v0 offset:3072
	v_add_u32_e32 v0, s22, v209
	ds_read_b128 v[154:157], v0
	ds_read_b128 v[158:161], v0 offset:1024
	ds_read_b128 v[162:165], v0 offset:2048
	ds_read_b128 v[166:169], v0 offset:3072
	v_lshl_add_u64 v[2:3], v[134:135], 0, s[88:89]
	s_add_i32 m0, s11, 0xc000
	ds_read_b128 v[170:173], v224
	ds_read_b128 v[174:177], v224 offset:1024
	ds_read_b128 v[194:197], v224 offset:2048
	ds_read_b128 v[198:201], v224 offset:3072
	ds_read_b128 v[202:205], v224 offset:4096
	ds_read_b128 v[226:229], v224 offset:5120
	ds_read_b128 v[230:233], v224 offset:6144
	ds_read_b128 v[234:237], v224 offset:7168
	global_load_lds_dwordx4 v[2:3], off
	v_lshl_add_u64 v[2:3], v[136:137], 0, s[88:89]
	s_add_i32 m0, s11, 0xe000
	s_nop 0
	global_load_lds_dwordx4 v[2:3], off
	s_waitcnt vmcnt(8)
	s_waitcnt lgkmcnt(0)
	s_barrier
	s_waitcnt lgkmcnt(0)
	v_mfma_f32_16x16x32_bf16 v[128:131], v[138:141], v[170:173], v[128:131]
	v_mfma_f32_16x16x32_bf16 v[124:127], v[146:149], v[170:173], v[124:127]
	v_mfma_f32_16x16x32_bf16 v[112:115], v[138:141], v[194:197], v[112:115]
	v_mfma_f32_16x16x32_bf16 v[108:111], v[146:149], v[194:197], v[108:111]
	v_mfma_f32_16x16x32_bf16 v[96:99], v[138:141], v[202:205], v[96:99]
	v_mfma_f32_16x16x32_bf16 v[92:95], v[146:149], v[202:205], v[92:95]
	v_mfma_f32_16x16x32_bf16 v[80:83], v[138:141], v[230:233], v[80:83]
	v_mfma_f32_16x16x32_bf16 v[76:79], v[146:149], v[230:233], v[76:79]
	v_mfma_f32_16x16x32_bf16 v[128:131], v[142:145], v[174:177], v[128:131]
	v_mfma_f32_16x16x32_bf16 v[124:127], v[150:153], v[174:177], v[124:127]
	v_mfma_f32_16x16x32_bf16 v[112:115], v[142:145], v[198:201], v[112:115]
	v_mfma_f32_16x16x32_bf16 v[108:111], v[150:153], v[198:201], v[108:111]
	v_mfma_f32_16x16x32_bf16 v[96:99], v[142:145], v[226:229], v[96:99]
	v_mfma_f32_16x16x32_bf16 v[92:95], v[150:153], v[226:229], v[92:95]
	v_mfma_f32_16x16x32_bf16 v[80:83], v[142:145], v[234:237], v[80:83]
	v_mfma_f32_16x16x32_bf16 v[76:79], v[150:153], v[234:237], v[76:79]
	v_mfma_f32_16x16x32_bf16 v[120:123], v[154:157], v[170:173], v[120:123]
	v_mfma_f32_16x16x32_bf16 v[116:119], v[162:165], v[170:173], v[116:119]
	v_mfma_f32_16x16x32_bf16 v[104:107], v[154:157], v[194:197], v[104:107]
	v_mfma_f32_16x16x32_bf16 v[100:103], v[162:165], v[194:197], v[100:103]
	v_mfma_f32_16x16x32_bf16 v[88:91], v[154:157], v[202:205], v[88:91]
	v_mfma_f32_16x16x32_bf16 v[84:87], v[162:165], v[202:205], v[84:87]
	v_mfma_f32_16x16x32_bf16 v[72:75], v[154:157], v[230:233], v[72:75]
	v_mfma_f32_16x16x32_bf16 v[68:71], v[162:165], v[230:233], v[68:71]
	v_mfma_f32_16x16x32_bf16 v[120:123], v[158:161], v[174:177], v[120:123]
	v_mfma_f32_16x16x32_bf16 v[116:119], v[166:169], v[174:177], v[116:119]
	v_mfma_f32_16x16x32_bf16 v[104:107], v[158:161], v[198:201], v[104:107]
	v_mfma_f32_16x16x32_bf16 v[100:103], v[166:169], v[198:201], v[100:103]
	v_mfma_f32_16x16x32_bf16 v[88:91], v[158:161], v[226:229], v[88:91]
	v_mfma_f32_16x16x32_bf16 v[84:87], v[166:169], v[226:229], v[84:87]
	v_mfma_f32_16x16x32_bf16 v[72:75], v[158:161], v[234:237], v[72:75]
	v_mfma_f32_16x16x32_bf16 v[68:71], v[166:169], v[234:237], v[68:71]
	s_barrier
	s_add_i32 s4, s4, s10
	v_lshl_add_u64 v[178:179], s[54:55], 0, v[184:185]
	s_mov_b32 m0, s4
	ds_read_b128 v[170:173], v224 offset:16384
	ds_read_b128 v[174:177], v224 offset:17408
	ds_read_b128 v[194:197], v224 offset:18432
	ds_read_b128 v[198:201], v224 offset:19456
	ds_read_b128 v[202:205], v224 offset:20480
	ds_read_b128 v[226:229], v224 offset:21504
	ds_read_b128 v[230:233], v224 offset:22528
	ds_read_b128 v[234:237], v224 offset:23552
	global_load_lds_dwordx4 v[178:179], off
	s_add_i32 m0, s4, 0x2000
	s_add_u32 s4, s54, 0x40000
	v_lshl_add_u64 v[206:207], s[54:55], 0, v[180:181]
	s_addc_u32 s5, s55, 0
	s_add_i32 s22, s22, s10
	global_load_lds_dwordx4 v[206:207], off
	v_lshl_add_u64 v[2:3], s[4:5], 0, v[184:185]
	s_mov_b32 m0, s22
	v_lshl_add_u64 v[242:243], s[90:91], 0, v[186:187]
	global_load_lds_dwordx4 v[2:3], off
	v_lshl_add_u64 v[2:3], s[4:5], 0, v[180:181]
	s_add_i32 m0, s22, 0x2000
	v_lshl_add_u64 v[244:245], s[90:91], 0, v[182:183]
	global_load_lds_dwordx4 v[2:3], off
	s_mov_b32 m0, s11
	s_nop 0
	global_load_lds_dwordx4 v[242:243], off
	s_mov_b32 m0, s12
	s_nop 0
	global_load_lds_dwordx4 v[244:245], off
	s_waitcnt vmcnt(8)
	s_waitcnt lgkmcnt(0)
	s_barrier
; #define PG8_STAGE(bufoff, gbase, voff) do { _Pragma("unroll") for (int _i = 0; _i < 2; ++_i) \
;         __builtin_amdgcn_global_load_lds((const unsigned*)((const char*)(gbase) + (voff)[_i]), (PG8_LAS unsigned*)(lds + (bufoff) + ldsw + _i * 8192), 16, 0, 0); } while (0)
; #define PG8_LDA(dst, b, h) do { _Pragma("unroll") for (int m = 0; m < 4; ++m) _Pragma("unroll") for (int k = 0; k < 2; ++k) dst[m][k] = *(const PG8_LAS bf16x8*)(lds + PG8_SA(b, h) + aoff + m * 2048 + k * 1024); } while (0)
; #define PG8_LDB(dst, b, h) do { _Pragma("unroll") for (int n = 0; n < 2; ++n) _Pragma("unroll") for (int k = 0; k < 2; ++k) dst[n][k] = *(const PG8_LAS bf16x8*)(lds + PG8_SB(b, h) + boff + n * 2048 + k * 1024); } while (0)
; #define PG8_MMA(ai, bj, At, Bt) do { __builtin_amdgcn_s_setprio(1); _Pragma("unroll") for (int m = 0; m < 4; ++m) _Pragma("unroll") for (int n = 0; n < 2; ++n) _Pragma("unroll") for (int k = 0; k < 2; ++k) \
;         acc[ai][bj][m][n] = __builtin_amdgcn_mfma_f32_16x16x32_bf16(Bt[n][k], At[m][k], acc[ai][bj][m][n], 0, 0, 0); __builtin_amdgcn_s_setprio(0); } while (0)
; #define PG8_WAIT_V(n) asm volatile("s_waitcnt vmcnt(" #n ")" ::: "memory")
; #define PG8_WAIT_L(n) asm volatile("s_waitcnt lgkmcnt(" #n ")" ::: "memory")
; #define PG8_BAR __builtin_amdgcn_s_barrier()
; #define PG8_SCHED __builtin_amdgcn_sched_barrier(0)
; template <class Epi, class Sched, bool ALIGN_EPI = false>
; __device__ __forceinline__ void gemm_phase(PG8_LAS unsigned char* lds, const Gemm g, const Sched& S, const Epi& E) {
;     ...
;             PG8_WAIT_V(8); PG8_WAIT_L(0); PG8_BAR; PG8_MMA(1, 0, At, B0); PG8_MMA(1, 1, At, B1); PG8_BAR; PG8_SCHED;
;             PG8_LDB(B0, 1, 0); PG8_LDB(B1, 1, 1); PG8_SCHED; PG8_LDA(At, 1, 0); PG8_STAGE(PG8_SA(0, 1), a2 + hstep, voffA);
;             PG8_WAIT_V(8); PG8_WAIT_L(0); PG8_BAR; PG8_MMA(0, 0, At, B0); PG8_MMA(0, 1, At, B1); PG8_BAR; PG8_SCHED;
	s_waitcnt lgkmcnt(0)
	v_mfma_f32_16x16x32_bf16 v[64:67], v[138:141], v[170:173], v[64:67]
	v_mfma_f32_16x16x32_bf16 v[60:63], v[146:149], v[170:173], v[60:63]
	v_mfma_f32_16x16x32_bf16 v[48:51], v[138:141], v[194:197], v[48:51]
	v_mfma_f32_16x16x32_bf16 v[44:47], v[146:149], v[194:197], v[44:47]
	v_mfma_f32_16x16x32_bf16 v[32:35], v[138:141], v[202:205], v[32:35]
	v_mfma_f32_16x16x32_bf16 v[28:31], v[146:149], v[202:205], v[28:31]
	v_mfma_f32_16x16x32_bf16 v[16:19], v[138:141], v[230:233], v[16:19]
	v_mfma_f32_16x16x32_bf16 v[12:15], v[146:149], v[230:233], v[12:15]
	v_mfma_f32_16x16x32_bf16 v[64:67], v[142:145], v[174:177], v[64:67]
	v_mfma_f32_16x16x32_bf16 v[60:63], v[150:153], v[174:177], v[60:63]
	v_mfma_f32_16x16x32_bf16 v[48:51], v[142:145], v[198:201], v[48:51]
	v_mfma_f32_16x16x32_bf16 v[44:47], v[150:153], v[198:201], v[44:47]
	v_mfma_f32_16x16x32_bf16 v[32:35], v[142:145], v[226:229], v[32:35]
	v_mfma_f32_16x16x32_bf16 v[28:31], v[150:153], v[226:229], v[28:31]
	v_mfma_f32_16x16x32_bf16 v[16:19], v[142:145], v[234:237], v[16:19]
	v_mfma_f32_16x16x32_bf16 v[12:15], v[150:153], v[234:237], v[12:15]
	v_mfma_f32_16x16x32_bf16 v[56:59], v[154:157], v[170:173], v[56:59]
	v_mfma_f32_16x16x32_bf16 v[52:55], v[162:165], v[170:173], v[52:55]
	v_mfma_f32_16x16x32_bf16 v[40:43], v[154:157], v[194:197], v[40:43]
	v_mfma_f32_16x16x32_bf16 v[36:39], v[162:165], v[194:197], v[36:39]
	v_mfma_f32_16x16x32_bf16 v[24:27], v[154:157], v[202:205], v[24:27]
	v_mfma_f32_16x16x32_bf16 v[20:23], v[162:165], v[202:205], v[20:23]
	v_mfma_f32_16x16x32_bf16 v[8:11], v[154:157], v[230:233], v[8:11]
	v_mfma_f32_16x16x32_bf16 v[2:5], v[162:165], v[230:233], v[4:7]
	v_mfma_f32_16x16x32_bf16 v[56:59], v[158:161], v[174:177], v[56:59]
	v_mfma_f32_16x16x32_bf16 v[52:55], v[166:169], v[174:177], v[52:55]
	v_mfma_f32_16x16x32_bf16 v[40:43], v[158:161], v[198:201], v[40:43]
	v_mfma_f32_16x16x32_bf16 v[36:39], v[166:169], v[198:201], v[36:39]
	v_mfma_f32_16x16x32_bf16 v[24:27], v[158:161], v[226:229], v[24:27]
	v_mfma_f32_16x16x32_bf16 v[20:23], v[166:169], v[226:229], v[20:23]
	v_mfma_f32_16x16x32_bf16 v[8:11], v[158:161], v[234:237], v[8:11]
	v_mfma_f32_16x16x32_bf16 v[2:5], v[166:169], v[234:237], v[2:5]
	s_barrier
	s_add_i32 s22, 0, 0x18000
	v_add_u32_e32 v0, s22, v209
	s_add_i32 s23, 0, 0x1c000
	ds_read_b128 v[138:141], v0
	ds_read_b128 v[142:145], v0 offset:1024
	ds_read_b128 v[146:149], v0 offset:2048
	ds_read_b128 v[150:153], v0 offset:3072
	v_add_u32_e32 v0, s23, v209
	ds_read_b128 v[154:157], v0
	ds_read_b128 v[158:161], v0 offset:1024
	ds_read_b128 v[162:165], v0 offset:2048
	ds_read_b128 v[166:169], v0 offset:3072
	s_add_u32 s4, s90, 0x40000
	s_addc_u32 s5, s91, 0
	s_mov_b32 m0, s13
	v_lshl_add_u64 v[6:7], s[4:5], 0, v[186:187]
	ds_read_b128 v[170:173], v224 offset:32768
	ds_read_b128 v[174:177], v224 offset:33792
	ds_read_b128 v[194:197], v224 offset:34816
	ds_read_b128 v[198:201], v224 offset:35840
	ds_read_b128 v[202:205], v224 offset:36864
	ds_read_b128 v[226:229], v224 offset:37888
	ds_read_b128 v[230:233], v224 offset:38912
	ds_read_b128 v[234:237], v224 offset:39936
	global_load_lds_dwordx4 v[6:7], off
	v_lshl_add_u64 v[6:7], s[4:5], 0, v[182:183]
	s_mov_b32 m0, s14
	s_nop 0
	global_load_lds_dwordx4 v[6:7], off
	s_waitcnt vmcnt(8)
	s_waitcnt lgkmcnt(0)
	s_barrier
	s_waitcnt lgkmcnt(0)
	v_mfma_f32_16x16x32_bf16 v[128:131], v[138:141], v[170:173], v[128:131]
	v_mfma_f32_16x16x32_bf16 v[124:127], v[146:149], v[170:173], v[124:127]
	v_mfma_f32_16x16x32_bf16 v[112:115], v[138:141], v[194:197], v[112:115]
	v_mfma_f32_16x16x32_bf16 v[108:111], v[146:149], v[194:197], v[108:111]
	v_mfma_f32_16x16x32_bf16 v[96:99], v[138:141], v[202:205], v[96:99]
	v_mfma_f32_16x16x32_bf16 v[92:95], v[146:149], v[202:205], v[92:95]
	v_mfma_f32_16x16x32_bf16 v[80:83], v[138:141], v[230:233], v[80:83]
	v_mfma_f32_16x16x32_bf16 v[76:79], v[146:149], v[230:233], v[76:79]
	v_mfma_f32_16x16x32_bf16 v[128:131], v[142:145], v[174:177], v[128:131]
	v_mfma_f32_16x16x32_bf16 v[124:127], v[150:153], v[174:177], v[124:127]
	v_mfma_f32_16x16x32_bf16 v[112:115], v[142:145], v[198:201], v[112:115]
	v_mfma_f32_16x16x32_bf16 v[108:111], v[150:153], v[198:201], v[108:111]
	v_mfma_f32_16x16x32_bf16 v[96:99], v[142:145], v[226:229], v[96:99]
	v_mfma_f32_16x16x32_bf16 v[92:95], v[150:153], v[226:229], v[92:95]
	v_mfma_f32_16x16x32_bf16 v[80:83], v[142:145], v[234:237], v[80:83]
	v_mfma_f32_16x16x32_bf16 v[76:79], v[150:153], v[234:237], v[76:79]
	v_mfma_f32_16x16x32_bf16 v[120:123], v[154:157], v[170:173], v[120:123]
	v_mfma_f32_16x16x32_bf16 v[116:119], v[162:165], v[170:173], v[116:119]
	v_mfma_f32_16x16x32_bf16 v[104:107], v[154:157], v[194:197], v[104:107]
	v_mfma_f32_16x16x32_bf16 v[100:103], v[162:165], v[194:197], v[100:103]
	v_mfma_f32_16x16x32_bf16 v[88:91], v[154:157], v[202:205], v[88:91]
	v_mfma_f32_16x16x32_bf16 v[84:87], v[162:165], v[202:205], v[84:87]
	v_mfma_f32_16x16x32_bf16 v[72:75], v[154:157], v[230:233], v[72:75]
	v_mfma_f32_16x16x32_bf16 v[68:71], v[162:165], v[230:233], v[68:71]
	v_mfma_f32_16x16x32_bf16 v[120:123], v[158:161], v[174:177], v[120:123]
	v_mfma_f32_16x16x32_bf16 v[116:119], v[166:169], v[174:177], v[116:119]
	v_mfma_f32_16x16x32_bf16 v[104:107], v[158:161], v[198:201], v[104:107]
	v_mfma_f32_16x16x32_bf16 v[100:103], v[166:169], v[198:201], v[100:103]
	v_mfma_f32_16x16x32_bf16 v[88:91], v[158:161], v[226:229], v[88:91]
	v_mfma_f32_16x16x32_bf16 v[84:87], v[166:169], v[226:229], v[84:87]
	v_mfma_f32_16x16x32_bf16 v[72:75], v[158:161], v[234:237], v[72:75]
	v_mfma_f32_16x16x32_bf16 v[68:71], v[166:169], v[234:237], v[68:71]
	s_barrier
; #define PG8_STAGE(bufoff, gbase, voff) do { _Pragma("unroll") for (int _i = 0; _i < 2; ++_i) \
;         __builtin_amdgcn_global_load_lds((const unsigned*)((const char*)(gbase) + (voff)[_i]), (PG8_LAS unsigned*)(lds + (bufoff) + ldsw + _i * 8192), 16, 0, 0); } while (0)
; #define PG8_LDA(dst, b, h) do { _Pragma("unroll") for (int m = 0; m < 4; ++m) _Pragma("unroll") for (int k = 0; k < 2; ++k) dst[m][k] = *(const PG8_LAS bf16x8*)(lds + PG8_SA(b, h) + aoff + m * 2048 + k * 1024); } while (0)
; #define PG8_MMA(ai, bj, At, Bt) do { __builtin_amdgcn_s_setprio(1); _Pragma("unroll") for (int m = 0; m < 4; ++m) _Pragma("unroll") for (int n = 0; n < 2; ++n) _Pragma("unroll") for (int k = 0; k < 2; ++k) \
;         acc[ai][bj][m][n] = __builtin_amdgcn_mfma_f32_16x16x32_bf16(Bt[n][k], At[m][k], acc[ai][bj][m][n], 0, 0, 0); __builtin_amdgcn_s_setprio(0); } while (0)
; #define PG8_WAIT_V(n) asm volatile("s_waitcnt vmcnt(" #n ")" ::: "memory")
; #define PG8_WAIT_L(n) asm volatile("s_waitcnt lgkmcnt(" #n ")" ::: "memory")
; #define PG8_BAR __builtin_amdgcn_s_barrier()
; #define PG8_SCHED __builtin_amdgcn_sched_barrier(0)
; template <class Epi, class Sched, bool ALIGN_EPI = false>
; __device__ __forceinline__ void gemm_phase(PG8_LAS unsigned char* lds, const Gemm g, const Sched& S, const Epi& E) {
;     ...
;             PG8_LDA(At, 1, 1); PG8_STAGE(PG8_SB(1, 0), b3, voffB); PG8_STAGE(PG8_SB(1, 1), b3 + hstep, voffB); PG8_STAGE(PG8_SA(1, 0), a3, voffA);
;             PG8_WAIT_V(8); PG8_WAIT_L(0); PG8_BAR; PG8_MMA(1, 0, At, B0); PG8_MMA(1, 1, At, B1); PG8_BAR; PG8_SCHED;
;         }
	s_add_i32 s4, s22, s10
	v_lshl_add_u64 v[6:7], v[178:179], 0, s[34:35]
	s_mov_b32 m0, s4
	ds_read_b128 v[170:173], v224 offset:49152
	ds_read_b128 v[174:177], v224 offset:50176
	ds_read_b128 v[194:197], v224 offset:51200
	ds_read_b128 v[198:201], v224 offset:52224
	ds_read_b128 v[202:205], v224 offset:53248
	ds_read_b128 v[226:229], v224 offset:54272
	ds_read_b128 v[230:233], v224 offset:55296
	ds_read_b128 v[234:237], v224 offset:56320
	global_load_lds_dwordx4 v[6:7], off
	s_add_i32 m0, s4, 0x2000
	s_add_u32 s4, s54, 0x40080
	v_lshl_add_u64 v[6:7], v[206:207], 0, s[34:35]
	s_addc_u32 s5, s55, 0
	s_add_i32 s22, s23, s10
	global_load_lds_dwordx4 v[6:7], off
	v_lshl_add_u64 v[6:7], s[4:5], 0, v[184:185]
	s_mov_b32 m0, s22
	s_nop 0
	global_load_lds_dwordx4 v[6:7], off
	v_lshl_add_u64 v[6:7], s[4:5], 0, v[180:181]
	s_add_i32 m0, s22, 0x2000
	s_nop 0
	global_load_lds_dwordx4 v[6:7], off
	v_lshl_add_u64 v[6:7], v[242:243], 0, s[34:35]
	s_mov_b32 m0, s15
	s_nop 0
	global_load_lds_dwordx4 v[6:7], off
	v_lshl_add_u64 v[6:7], v[244:245], 0, s[34:35]
	s_mov_b32 m0, s16
	s_nop 0
	global_load_lds_dwordx4 v[6:7], off
	s_waitcnt vmcnt(8)
	s_waitcnt lgkmcnt(0)
	s_barrier
	s_waitcnt lgkmcnt(0)
	v_mfma_f32_16x16x32_bf16 v[64:67], v[138:141], v[170:173], v[64:67]
	v_mfma_f32_16x16x32_bf16 v[60:63], v[146:149], v[170:173], v[60:63]
	v_mfma_f32_16x16x32_bf16 v[48:51], v[138:141], v[194:197], v[48:51]
	v_mfma_f32_16x16x32_bf16 v[44:47], v[146:149], v[194:197], v[44:47]
	v_mfma_f32_16x16x32_bf16 v[32:35], v[138:141], v[202:205], v[32:35]
	v_mfma_f32_16x16x32_bf16 v[28:31], v[146:149], v[202:205], v[28:31]
	v_mfma_f32_16x16x32_bf16 v[16:19], v[138:141], v[230:233], v[16:19]
	v_mfma_f32_16x16x32_bf16 v[12:15], v[146:149], v[230:233], v[12:15]
	v_mfma_f32_16x16x32_bf16 v[64:67], v[142:145], v[174:177], v[64:67]
	v_mfma_f32_16x16x32_bf16 v[60:63], v[150:153], v[174:177], v[60:63]
	v_mfma_f32_16x16x32_bf16 v[48:51], v[142:145], v[198:201], v[48:51]
	v_mfma_f32_16x16x32_bf16 v[44:47], v[150:153], v[198:201], v[44:47]
	v_mfma_f32_16x16x32_bf16 v[32:35], v[142:145], v[226:229], v[32:35]
	v_mfma_f32_16x16x32_bf16 v[28:31], v[150:153], v[226:229], v[28:31]
	v_mfma_f32_16x16x32_bf16 v[16:19], v[142:145], v[234:237], v[16:19]
	v_mfma_f32_16x16x32_bf16 v[12:15], v[150:153], v[234:237], v[12:15]
	v_mfma_f32_16x16x32_bf16 v[56:59], v[154:157], v[170:173], v[56:59]
	v_mfma_f32_16x16x32_bf16 v[52:55], v[162:165], v[170:173], v[52:55]
	v_mfma_f32_16x16x32_bf16 v[40:43], v[154:157], v[194:197], v[40:43]
	v_mfma_f32_16x16x32_bf16 v[36:39], v[162:165], v[194:197], v[36:39]
	v_mfma_f32_16x16x32_bf16 v[24:27], v[154:157], v[202:205], v[24:27]
	v_mfma_f32_16x16x32_bf16 v[20:23], v[162:165], v[202:205], v[20:23]
	v_mfma_f32_16x16x32_bf16 v[6:9], v[154:157], v[230:233], v[8:11]
	v_mfma_f32_16x16x32_bf16 v[2:5], v[162:165], v[230:233], v[2:5]
	v_mfma_f32_16x16x32_bf16 v[56:59], v[158:161], v[174:177], v[56:59]
	v_mfma_f32_16x16x32_bf16 v[52:55], v[166:169], v[174:177], v[52:55]
	v_mfma_f32_16x16x32_bf16 v[40:43], v[158:161], v[198:201], v[40:43]
	v_mfma_f32_16x16x32_bf16 v[36:39], v[166:169], v[198:201], v[36:39]
	v_mfma_f32_16x16x32_bf16 v[24:27], v[158:161], v[226:229], v[24:27]
	v_mfma_f32_16x16x32_bf16 v[20:23], v[166:169], v[226:229], v[20:23]
	v_mfma_f32_16x16x32_bf16 v[8:11], v[158:161], v[234:237], v[6:9]
	v_mfma_f32_16x16x32_bf16 v[4:7], v[166:169], v[234:237], v[2:5]
	s_barrier
	s_add_i32 s92, s92, 2
	s_add_u32 s88, s88, 0x100
	s_addc_u32 s89, s89, 0
	s_cmp_gt_u32 s92, 13
	s_cbranch_scc1 .LBB0_1202
